# RG-LRU gate+scan phase rewritten: one wave per channel block, in-register time scan, no workgroup barriers; plus in-proj write-through stores and flat-release barrier
# speedup vs baseline: 1.0705x; 1.0088x over previous
.LBB0_322:
	s_waitcnt lgkmcnt(0)
	s_barrier
	v_lshrrev_b32_e32 v140, 6, v154
	v_and_b32_e32 v141, 15, v154
	v_bfe_u32 v142, v154, 4, 2
	v_and_b32_e32 v145, 63, v154
	v_readfirstlane_b32 s4, v140
	s_lshl_b32 s5, s4, 13
	s_add_u32 s6, s44, 0x1e40000
	s_addc_u32 s7, s45, 0
	s_add_u32 s6, s6, s5
	s_addc_u32 s7, s7, 0
	s_add_u32 s8, s6, 0x10000
	s_addc_u32 s9, s7, 0
	s_lshl_b32 s10, s18, 10
	s_lshl_b32 s11, s4, 7
	s_add_u32 s10, s10, s11
	s_add_u32 s10, s10, 0x2300000
	s_add_u32 s10, s44, s10
	s_addc_u32 s11, s45, 0
	s_add_u32 s12, s10, 0x1000000
	s_addc_u32 s13, s11, 0
	s_lshl_b32 s14, s3, 11
	s_lshl_b32 s15, s4, 8
	s_add_u32 s14, s14, s15
	s_add_u32 s14, s14, 0xfc00000
	s_add_u32 s14, s44, s14
	s_addc_u32 s15, s45, 0
	s_add_u32 s16, s14, 0x80000
	s_addc_u32 s17, s15, 0
	s_mov_b32 s94, 0xffff0000
	s_mov_b32 s95, -1
	s_mov_b32 s96, 0
	s_mov_b32 s97, -1
	s_mov_b32 s98, 0
	s_mov_b32 s99, 0xffff0000
	s_lshl_b32 s19, s4, 13
	s_add_u32 s19, s19, 0x10400
	s_cmp_lt_u32 s4, 4
	s_cselect_b32 s5, 0, 0x2a00
	s_add_u32 s19, s19, s5
	v_lshlrev_b32_e32 v143, 7, v141
	v_lshl_or_b32 v143, v142, 4, v143
	v_add_u32_e32 v144, 0x1000, v143
	global_load_dwordx4 v[32:35], v143, s[6:7]
	global_load_dwordx4 v[36:39], v143, s[6:7] offset:64
	global_load_dwordx4 v[40:43], v143, s[6:7] offset:2048
	global_load_dwordx4 v[44:47], v143, s[6:7] offset:2112
	global_load_dwordx4 v[52:55], v144, s[6:7]
	global_load_dwordx4 v[56:59], v144, s[6:7] offset:64
	global_load_dwordx4 v[60:63], v144, s[6:7] offset:2048
	global_load_dwordx4 v[252:255], v144, s[6:7] offset:2112
	global_load_dwordx4 v[220:223], v143, s[8:9]
	global_load_dwordx4 v[224:227], v143, s[8:9] offset:64
	global_load_dwordx4 v[228:231], v143, s[8:9] offset:2048
	global_load_dwordx4 v[232:235], v143, s[8:9] offset:2112
	global_load_dwordx4 v[236:239], v144, s[8:9]
	global_load_dwordx4 v[240:243], v144, s[8:9] offset:64
	global_load_dwordx4 v[244:247], v144, s[8:9] offset:2048
	global_load_dwordx4 v[248:251], v144, s[8:9] offset:2112
	s_lshl_b32 s5, s4, 7
	v_lshrrev_b32_e32 v148, 2, v141
	v_and_b32_e32 v149, 3, v141
	v_lshl_or_b32 v148, v148, 4, v149
	v_mul_u32_u24_e32 v146, 0x410, v148
	v_lshl_add_u32 v146, v142, 4, v146
	v_add_u32_e32 v146, s5, v146
	ds_read_b128 v[0:3], v146
	ds_read_b128 v[4:7], v146 offset:64
	ds_read_b128 v[8:11], v146 offset:4160
	ds_read_b128 v[12:15], v146 offset:4224
	ds_read_b128 v[16:19], v146 offset:8320
	ds_read_b128 v[20:23], v146 offset:8384
	ds_read_b128 v[24:27], v146 offset:12480
	ds_read_b128 v[28:31], v146 offset:12544
	v_mul_u32_u24_e32 v147, 0x4100, v142
	v_lshl_add_u32 v147, v141, 1, v147
	v_add_u32_e32 v147, s5, v147
	s_lshl_b32 s5, s4, 8
	v_lshl_add_u32 v140, v141, 2, s5
	v_add_u32_e32 v140, 0x19600, v140
	ds_read_b32 v132, v140 offset:0
	ds_read_b32 v128, v140 offset:2048
	ds_read_b32 v136, v140 offset:4096
	ds_read_b32 v133, v140 offset:64
	ds_read_b32 v129, v140 offset:2112
	ds_read_b32 v137, v140 offset:4160
	ds_read_b32 v134, v140 offset:128
	ds_read_b32 v130, v140 offset:2176
	ds_read_b32 v138, v140 offset:4224
	ds_read_b32 v135, v140 offset:192
	ds_read_b32 v131, v140 offset:2240
	ds_read_b32 v139, v140 offset:4288
	s_waitcnt vmcnt(8) lgkmcnt(0)
	v_mfma_f32_16x16x32_bf16 v[64:67], v[0:3], v[32:35], 0
	v_mfma_f32_16x16x32_bf16 v[80:83], v[0:3], v[40:43], 0
	v_mfma_f32_16x16x32_bf16 v[96:99], v[0:3], v[52:55], 0
	v_mfma_f32_16x16x32_bf16 v[112:115], v[0:3], v[60:63], 0
	v_mfma_f32_16x16x32_bf16 v[68:71], v[8:11], v[32:35], 0
	v_mfma_f32_16x16x32_bf16 v[84:87], v[8:11], v[40:43], 0
	v_mfma_f32_16x16x32_bf16 v[100:103], v[8:11], v[52:55], 0
	v_mfma_f32_16x16x32_bf16 v[116:119], v[8:11], v[60:63], 0
	v_mfma_f32_16x16x32_bf16 v[72:75], v[16:19], v[32:35], 0
	v_mfma_f32_16x16x32_bf16 v[88:91], v[16:19], v[40:43], 0
	v_mfma_f32_16x16x32_bf16 v[104:107], v[16:19], v[52:55], 0
	v_mfma_f32_16x16x32_bf16 v[120:123], v[16:19], v[60:63], 0
	v_mfma_f32_16x16x32_bf16 v[76:79], v[24:27], v[32:35], 0
	v_mfma_f32_16x16x32_bf16 v[92:95], v[24:27], v[40:43], 0
	v_mfma_f32_16x16x32_bf16 v[108:111], v[24:27], v[52:55], 0
	v_mfma_f32_16x16x32_bf16 v[124:127], v[24:27], v[60:63], 0
	v_mfma_f32_16x16x32_bf16 v[64:67], v[4:7], v[36:39], v[64:67]
	v_mfma_f32_16x16x32_bf16 v[80:83], v[4:7], v[44:47], v[80:83]
	v_mfma_f32_16x16x32_bf16 v[96:99], v[4:7], v[56:59], v[96:99]
	v_mfma_f32_16x16x32_bf16 v[112:115], v[4:7], v[252:255], v[112:115]
	v_mfma_f32_16x16x32_bf16 v[68:71], v[12:15], v[36:39], v[68:71]
	v_mfma_f32_16x16x32_bf16 v[84:87], v[12:15], v[44:47], v[84:87]
	v_mfma_f32_16x16x32_bf16 v[100:103], v[12:15], v[56:59], v[100:103]
	v_mfma_f32_16x16x32_bf16 v[116:119], v[12:15], v[252:255], v[116:119]
	v_mfma_f32_16x16x32_bf16 v[72:75], v[20:23], v[36:39], v[72:75]
	v_mfma_f32_16x16x32_bf16 v[88:91], v[20:23], v[44:47], v[88:91]
	v_mfma_f32_16x16x32_bf16 v[104:107], v[20:23], v[56:59], v[104:107]
	v_mfma_f32_16x16x32_bf16 v[120:123], v[20:23], v[252:255], v[120:123]
	v_mfma_f32_16x16x32_bf16 v[76:79], v[28:31], v[36:39], v[76:79]
	v_mfma_f32_16x16x32_bf16 v[92:95], v[28:31], v[44:47], v[92:95]
	v_mfma_f32_16x16x32_bf16 v[108:111], v[28:31], v[56:59], v[108:111]
	v_mfma_f32_16x16x32_bf16 v[124:127], v[28:31], v[252:255], v[124:127]
	s_waitcnt vmcnt(0)
	v_mfma_f32_16x16x32_bf16 v[156:159], v[0:3], v[220:223], 0
	v_mfma_f32_16x16x32_bf16 v[172:175], v[0:3], v[228:231], 0
	v_mfma_f32_16x16x32_bf16 v[188:191], v[0:3], v[236:239], 0
	v_mfma_f32_16x16x32_bf16 v[204:207], v[0:3], v[244:247], 0
	v_mfma_f32_16x16x32_bf16 v[160:163], v[8:11], v[220:223], 0
	v_mfma_f32_16x16x32_bf16 v[176:179], v[8:11], v[228:231], 0
	v_mfma_f32_16x16x32_bf16 v[192:195], v[8:11], v[236:239], 0
	v_mfma_f32_16x16x32_bf16 v[208:211], v[8:11], v[244:247], 0
	v_mfma_f32_16x16x32_bf16 v[164:167], v[16:19], v[220:223], 0
	v_mfma_f32_16x16x32_bf16 v[180:183], v[16:19], v[228:231], 0
	v_mfma_f32_16x16x32_bf16 v[196:199], v[16:19], v[236:239], 0
	v_mfma_f32_16x16x32_bf16 v[212:215], v[16:19], v[244:247], 0
	v_mfma_f32_16x16x32_bf16 v[168:171], v[24:27], v[220:223], 0
	v_mfma_f32_16x16x32_bf16 v[184:187], v[24:27], v[228:231], 0
	v_mfma_f32_16x16x32_bf16 v[200:203], v[24:27], v[236:239], 0
	v_mfma_f32_16x16x32_bf16 v[216:219], v[24:27], v[244:247], 0
	v_mfma_f32_16x16x32_bf16 v[156:159], v[4:7], v[224:227], v[156:159]
	v_mfma_f32_16x16x32_bf16 v[172:175], v[4:7], v[232:235], v[172:175]
	v_mfma_f32_16x16x32_bf16 v[188:191], v[4:7], v[240:243], v[188:191]
	v_mfma_f32_16x16x32_bf16 v[204:207], v[4:7], v[248:251], v[204:207]
	v_mfma_f32_16x16x32_bf16 v[160:163], v[12:15], v[224:227], v[160:163]
	v_mfma_f32_16x16x32_bf16 v[176:179], v[12:15], v[232:235], v[176:179]
	v_mfma_f32_16x16x32_bf16 v[192:195], v[12:15], v[240:243], v[192:195]
	v_mfma_f32_16x16x32_bf16 v[208:211], v[12:15], v[248:251], v[208:211]
	v_mfma_f32_16x16x32_bf16 v[164:167], v[20:23], v[224:227], v[164:167]
	v_mfma_f32_16x16x32_bf16 v[180:183], v[20:23], v[232:235], v[180:183]
	v_mfma_f32_16x16x32_bf16 v[196:199], v[20:23], v[240:243], v[196:199]
	v_mfma_f32_16x16x32_bf16 v[212:215], v[20:23], v[248:251], v[212:215]
	v_mfma_f32_16x16x32_bf16 v[168:171], v[28:31], v[224:227], v[168:171]
	v_mfma_f32_16x16x32_bf16 v[184:187], v[28:31], v[232:235], v[184:187]
	v_mfma_f32_16x16x32_bf16 v[200:203], v[28:31], v[240:243], v[200:203]
	v_mfma_f32_16x16x32_bf16 v[216:219], v[28:31], v[248:251], v[216:219]
	v_lshlrev_b32_e32 v220, 11, v142
	v_lshl_add_u32 v220, v141, 1, v220
	v_add_u32_e32 v220, s19, v220
	v_lshrrev_b32_e32 v148, 3, v145
	v_and_b32_e32 v149, 7, v145
	v_mul_u32_u24_e32 v221, 0x410, v148
	v_lshl_add_u32 v221, v149, 4, v221
	s_lshl_b32 s5, s4, 7
	v_add_u32_e32 v221, s5, v221
	v_lshlrev_b32_e32 v222, 7, v148
	v_lshl_add_u32 v222, v149, 4, v222
	v_add_u32_e32 v222, s19, v222
	v_lshlrev_b32_e32 v223, 10, v148
	v_lshl_add_u32 v223, v149, 4, v223
	v_lshlrev_b32_e32 v224, 2, v141
	v_add_u32_e32 v225, 48, v145
	v_and_b32_e32 v225, 63, v225
	v_lshlrev_b32_e32 v225, 2, v225
	v_add_u32_e32 v226, 32, v145
	v_and_b32_e32 v226, 63, v226
	v_lshlrev_b32_e32 v226, 2, v226
	v_add_u32_e32 v227, 16, v145
	v_and_b32_e32 v227, 63, v227
	v_lshlrev_b32_e32 v227, 2, v227
	ds_read_u16 v32, v147 offset:0
	ds_read_u16 v33, v147 offset:1040
	ds_read_u16 v34, v147 offset:2080
	ds_read_u16 v35, v147 offset:3120
	ds_read_u16 v36, v147 offset:4160
	ds_read_u16 v37, v147 offset:5200
	ds_read_u16 v38, v147 offset:6240
	ds_read_u16 v39, v147 offset:7280
	ds_read_u16 v40, v147 offset:8320
	ds_read_u16 v41, v147 offset:9360
	ds_read_u16 v42, v147 offset:10400
	ds_read_u16 v43, v147 offset:11440
	ds_read_u16 v44, v147 offset:12480
	ds_read_u16 v45, v147 offset:13520
	ds_read_u16 v46, v147 offset:14560
	ds_read_u16 v47, v147 offset:15600
	ds_read_u16 v52, v147 offset:32
	ds_read_u16 v53, v147 offset:1072
	ds_read_u16 v54, v147 offset:2112
	ds_read_u16 v55, v147 offset:3152
	ds_read_u16 v56, v147 offset:4192
	ds_read_u16 v57, v147 offset:5232
	ds_read_u16 v58, v147 offset:6272
	ds_read_u16 v59, v147 offset:7312
	ds_read_u16 v60, v147 offset:8352
	ds_read_u16 v61, v147 offset:9392
	ds_read_u16 v62, v147 offset:10432
	ds_read_u16 v63, v147 offset:11472
	ds_read_u16 v252, v147 offset:12512
	ds_read_u16 v253, v147 offset:13552
	ds_read_u16 v254, v147 offset:14592
	ds_read_u16 v255, v147 offset:15632
	v_add_f32_e32 v64, v64, v128
	v_add_f32_e32 v65, v65, v128
	v_add_f32_e32 v66, v66, v128
	v_add_f32_e32 v67, v67, v128
	v_add_f32_e32 v68, v68, v128
	v_add_f32_e32 v69, v69, v128
	v_add_f32_e32 v70, v70, v128
	v_add_f32_e32 v71, v71, v128
	v_mul_f32_e32 v64, 0xbfb8aa3b, v64
	v_mul_f32_e32 v65, 0xbfb8aa3b, v65
	v_mul_f32_e32 v66, 0xbfb8aa3b, v66
	v_mul_f32_e32 v67, 0xbfb8aa3b, v67
	v_mul_f32_e32 v68, 0xbfb8aa3b, v68
	v_mul_f32_e32 v69, 0xbfb8aa3b, v69
	v_mul_f32_e32 v70, 0xbfb8aa3b, v70
	v_mul_f32_e32 v71, 0xbfb8aa3b, v71
	v_exp_f32_e32 v64, v64
	v_exp_f32_e32 v65, v65
	v_exp_f32_e32 v66, v66
	v_exp_f32_e32 v67, v67
	v_exp_f32_e32 v68, v68
	v_exp_f32_e32 v69, v69
	v_exp_f32_e32 v70, v70
	v_exp_f32_e32 v71, v71
	v_add_f32_e32 v64, 1.0, v64
	v_add_f32_e32 v65, 1.0, v65
	v_add_f32_e32 v66, 1.0, v66
	v_add_f32_e32 v67, 1.0, v67
	v_add_f32_e32 v68, 1.0, v68
	v_add_f32_e32 v69, 1.0, v69
	v_add_f32_e32 v70, 1.0, v70
	v_add_f32_e32 v71, 1.0, v71
	v_rcp_f32_e32 v64, v64
	v_rcp_f32_e32 v65, v65
	v_rcp_f32_e32 v66, v66
	v_rcp_f32_e32 v67, v67
	v_rcp_f32_e32 v68, v68
	v_rcp_f32_e32 v69, v69
	v_rcp_f32_e32 v70, v70
	v_rcp_f32_e32 v71, v71
	v_mul_f32_e32 v64, 0x41000000, v64
	v_mul_f32_e32 v65, 0x41000000, v65
	v_mul_f32_e32 v66, 0x41000000, v66
	v_mul_f32_e32 v67, 0x41000000, v67
	v_mul_f32_e32 v68, 0x41000000, v68
	v_mul_f32_e32 v69, 0x41000000, v69
	v_mul_f32_e32 v70, 0x41000000, v70
	v_mul_f32_e32 v71, 0x41000000, v71
	v_mul_f32_e32 v64, v64, v132
	v_mul_f32_e32 v65, v65, v132
	v_mul_f32_e32 v66, v66, v132
	v_mul_f32_e32 v67, v67, v132
	v_mul_f32_e32 v68, v68, v132
	v_mul_f32_e32 v69, v69, v132
	v_mul_f32_e32 v70, v70, v132
	v_mul_f32_e32 v71, v71, v132
	v_mul_f32_e32 v64, 0x3fb8aa3b, v64
	v_mul_f32_e32 v65, 0x3fb8aa3b, v65
	v_mul_f32_e32 v66, 0x3fb8aa3b, v66
	v_mul_f32_e32 v67, 0x3fb8aa3b, v67
	v_mul_f32_e32 v68, 0x3fb8aa3b, v68
	v_mul_f32_e32 v69, 0x3fb8aa3b, v69
	v_mul_f32_e32 v70, 0x3fb8aa3b, v70
	v_mul_f32_e32 v71, 0x3fb8aa3b, v71
	v_exp_f32_e32 v64, v64
	v_exp_f32_e32 v65, v65
	v_exp_f32_e32 v66, v66
	v_exp_f32_e32 v67, v67
	v_exp_f32_e32 v68, v68
	v_exp_f32_e32 v69, v69
	v_exp_f32_e32 v70, v70
	v_exp_f32_e32 v71, v71
	v_add_f32_e32 v72, v72, v128
	v_add_f32_e32 v73, v73, v128
	v_add_f32_e32 v74, v74, v128
	v_add_f32_e32 v75, v75, v128
	v_add_f32_e32 v76, v76, v128
	v_add_f32_e32 v77, v77, v128
	v_add_f32_e32 v78, v78, v128
	v_add_f32_e32 v79, v79, v128
	v_mul_f32_e32 v72, 0xbfb8aa3b, v72
	v_mul_f32_e32 v73, 0xbfb8aa3b, v73
	v_mul_f32_e32 v74, 0xbfb8aa3b, v74
	v_mul_f32_e32 v75, 0xbfb8aa3b, v75
	v_mul_f32_e32 v76, 0xbfb8aa3b, v76
	v_mul_f32_e32 v77, 0xbfb8aa3b, v77
	v_mul_f32_e32 v78, 0xbfb8aa3b, v78
	v_mul_f32_e32 v79, 0xbfb8aa3b, v79
	v_exp_f32_e32 v72, v72
	v_exp_f32_e32 v73, v73
	v_exp_f32_e32 v74, v74
	v_exp_f32_e32 v75, v75
	v_exp_f32_e32 v76, v76
	v_exp_f32_e32 v77, v77
	v_exp_f32_e32 v78, v78
	v_exp_f32_e32 v79, v79
	v_add_f32_e32 v72, 1.0, v72
	v_add_f32_e32 v73, 1.0, v73
	v_add_f32_e32 v74, 1.0, v74
	v_add_f32_e32 v75, 1.0, v75
	v_add_f32_e32 v76, 1.0, v76
	v_add_f32_e32 v77, 1.0, v77
	v_add_f32_e32 v78, 1.0, v78
	v_add_f32_e32 v79, 1.0, v79
	v_rcp_f32_e32 v72, v72
	v_rcp_f32_e32 v73, v73
	v_rcp_f32_e32 v74, v74
	v_rcp_f32_e32 v75, v75
	v_rcp_f32_e32 v76, v76
	v_rcp_f32_e32 v77, v77
	v_rcp_f32_e32 v78, v78
	v_rcp_f32_e32 v79, v79
	v_mul_f32_e32 v72, 0x41000000, v72
	v_mul_f32_e32 v73, 0x41000000, v73
	v_mul_f32_e32 v74, 0x41000000, v74
	v_mul_f32_e32 v75, 0x41000000, v75
	v_mul_f32_e32 v76, 0x41000000, v76
	v_mul_f32_e32 v77, 0x41000000, v77
	v_mul_f32_e32 v78, 0x41000000, v78
	v_mul_f32_e32 v79, 0x41000000, v79
	v_mul_f32_e32 v72, v72, v132
	v_mul_f32_e32 v73, v73, v132
	v_mul_f32_e32 v74, v74, v132
	v_mul_f32_e32 v75, v75, v132
	v_mul_f32_e32 v76, v76, v132
	v_mul_f32_e32 v77, v77, v132
	v_mul_f32_e32 v78, v78, v132
	v_mul_f32_e32 v79, v79, v132
	v_mul_f32_e32 v72, 0x3fb8aa3b, v72
	v_mul_f32_e32 v73, 0x3fb8aa3b, v73
	v_mul_f32_e32 v74, 0x3fb8aa3b, v74
	v_mul_f32_e32 v75, 0x3fb8aa3b, v75
	v_mul_f32_e32 v76, 0x3fb8aa3b, v76
	v_mul_f32_e32 v77, 0x3fb8aa3b, v77
	v_mul_f32_e32 v78, 0x3fb8aa3b, v78
	v_mul_f32_e32 v79, 0x3fb8aa3b, v79
	v_exp_f32_e32 v72, v72
	v_exp_f32_e32 v73, v73
	v_exp_f32_e32 v74, v74
	v_exp_f32_e32 v75, v75
	v_exp_f32_e32 v76, v76
	v_exp_f32_e32 v77, v77
	v_exp_f32_e32 v78, v78
	v_exp_f32_e32 v79, v79
	v_add_f32_e32 v80, v80, v129
	v_add_f32_e32 v81, v81, v129
	v_add_f32_e32 v82, v82, v129
	v_add_f32_e32 v83, v83, v129
	v_add_f32_e32 v84, v84, v129
	v_add_f32_e32 v85, v85, v129
	v_add_f32_e32 v86, v86, v129
	v_add_f32_e32 v87, v87, v129
	v_mul_f32_e32 v80, 0xbfb8aa3b, v80
	v_mul_f32_e32 v81, 0xbfb8aa3b, v81
	v_mul_f32_e32 v82, 0xbfb8aa3b, v82
	v_mul_f32_e32 v83, 0xbfb8aa3b, v83
	v_mul_f32_e32 v84, 0xbfb8aa3b, v84
	v_mul_f32_e32 v85, 0xbfb8aa3b, v85
	v_mul_f32_e32 v86, 0xbfb8aa3b, v86
	v_mul_f32_e32 v87, 0xbfb8aa3b, v87
	v_exp_f32_e32 v80, v80
	v_exp_f32_e32 v81, v81
	v_exp_f32_e32 v82, v82
	v_exp_f32_e32 v83, v83
	v_exp_f32_e32 v84, v84
	v_exp_f32_e32 v85, v85
	v_exp_f32_e32 v86, v86
	v_exp_f32_e32 v87, v87
	v_add_f32_e32 v80, 1.0, v80
	v_add_f32_e32 v81, 1.0, v81
	v_add_f32_e32 v82, 1.0, v82
	v_add_f32_e32 v83, 1.0, v83
	v_add_f32_e32 v84, 1.0, v84
	v_add_f32_e32 v85, 1.0, v85
	v_add_f32_e32 v86, 1.0, v86
	v_add_f32_e32 v87, 1.0, v87
	v_rcp_f32_e32 v80, v80
	v_rcp_f32_e32 v81, v81
	v_rcp_f32_e32 v82, v82
	v_rcp_f32_e32 v83, v83
	v_rcp_f32_e32 v84, v84
	v_rcp_f32_e32 v85, v85
	v_rcp_f32_e32 v86, v86
	v_rcp_f32_e32 v87, v87
	v_mul_f32_e32 v80, 0x41000000, v80
	v_mul_f32_e32 v81, 0x41000000, v81
	v_mul_f32_e32 v82, 0x41000000, v82
	v_mul_f32_e32 v83, 0x41000000, v83
	v_mul_f32_e32 v84, 0x41000000, v84
	v_mul_f32_e32 v85, 0x41000000, v85
	v_mul_f32_e32 v86, 0x41000000, v86
	v_mul_f32_e32 v87, 0x41000000, v87
	v_mul_f32_e32 v80, v80, v133
	v_mul_f32_e32 v81, v81, v133
	v_mul_f32_e32 v82, v82, v133
	v_mul_f32_e32 v83, v83, v133
	v_mul_f32_e32 v84, v84, v133
	v_mul_f32_e32 v85, v85, v133
	v_mul_f32_e32 v86, v86, v133
	v_mul_f32_e32 v87, v87, v133
	v_mul_f32_e32 v80, 0x3fb8aa3b, v80
	v_mul_f32_e32 v81, 0x3fb8aa3b, v81
	v_mul_f32_e32 v82, 0x3fb8aa3b, v82
	v_mul_f32_e32 v83, 0x3fb8aa3b, v83
	v_mul_f32_e32 v84, 0x3fb8aa3b, v84
	v_mul_f32_e32 v85, 0x3fb8aa3b, v85
	v_mul_f32_e32 v86, 0x3fb8aa3b, v86
	v_mul_f32_e32 v87, 0x3fb8aa3b, v87
	v_exp_f32_e32 v80, v80
	v_exp_f32_e32 v81, v81
	v_exp_f32_e32 v82, v82
	v_exp_f32_e32 v83, v83
	v_exp_f32_e32 v84, v84
	v_exp_f32_e32 v85, v85
	v_exp_f32_e32 v86, v86
	v_exp_f32_e32 v87, v87
	v_add_f32_e32 v88, v88, v129
	v_add_f32_e32 v89, v89, v129
	v_add_f32_e32 v90, v90, v129
	v_add_f32_e32 v91, v91, v129
	v_add_f32_e32 v92, v92, v129
	v_add_f32_e32 v93, v93, v129
	v_add_f32_e32 v94, v94, v129
	v_add_f32_e32 v95, v95, v129
	v_mul_f32_e32 v88, 0xbfb8aa3b, v88
	v_mul_f32_e32 v89, 0xbfb8aa3b, v89
	v_mul_f32_e32 v90, 0xbfb8aa3b, v90
	v_mul_f32_e32 v91, 0xbfb8aa3b, v91
	v_mul_f32_e32 v92, 0xbfb8aa3b, v92
	v_mul_f32_e32 v93, 0xbfb8aa3b, v93
	v_mul_f32_e32 v94, 0xbfb8aa3b, v94
	v_mul_f32_e32 v95, 0xbfb8aa3b, v95
	v_exp_f32_e32 v88, v88
	v_exp_f32_e32 v89, v89
	v_exp_f32_e32 v90, v90
	v_exp_f32_e32 v91, v91
	v_exp_f32_e32 v92, v92
	v_exp_f32_e32 v93, v93
	v_exp_f32_e32 v94, v94
	v_exp_f32_e32 v95, v95
	v_add_f32_e32 v88, 1.0, v88
	v_add_f32_e32 v89, 1.0, v89
	v_add_f32_e32 v90, 1.0, v90
	v_add_f32_e32 v91, 1.0, v91
	v_add_f32_e32 v92, 1.0, v92
	v_add_f32_e32 v93, 1.0, v93
	v_add_f32_e32 v94, 1.0, v94
	v_add_f32_e32 v95, 1.0, v95
	v_rcp_f32_e32 v88, v88
	v_rcp_f32_e32 v89, v89
	v_rcp_f32_e32 v90, v90
	v_rcp_f32_e32 v91, v91
	v_rcp_f32_e32 v92, v92
	v_rcp_f32_e32 v93, v93
	v_rcp_f32_e32 v94, v94
	v_rcp_f32_e32 v95, v95
	v_mul_f32_e32 v88, 0x41000000, v88
	v_mul_f32_e32 v89, 0x41000000, v89
	v_mul_f32_e32 v90, 0x41000000, v90
	v_mul_f32_e32 v91, 0x41000000, v91
	v_mul_f32_e32 v92, 0x41000000, v92
	v_mul_f32_e32 v93, 0x41000000, v93
	v_mul_f32_e32 v94, 0x41000000, v94
	v_mul_f32_e32 v95, 0x41000000, v95
	v_mul_f32_e32 v88, v88, v133
	v_mul_f32_e32 v89, v89, v133
	v_mul_f32_e32 v90, v90, v133
	v_mul_f32_e32 v91, v91, v133
	v_mul_f32_e32 v92, v92, v133
	v_mul_f32_e32 v93, v93, v133
	v_mul_f32_e32 v94, v94, v133
	v_mul_f32_e32 v95, v95, v133
	v_mul_f32_e32 v88, 0x3fb8aa3b, v88
	v_mul_f32_e32 v89, 0x3fb8aa3b, v89
	v_mul_f32_e32 v90, 0x3fb8aa3b, v90
	v_mul_f32_e32 v91, 0x3fb8aa3b, v91
	v_mul_f32_e32 v92, 0x3fb8aa3b, v92
	v_mul_f32_e32 v93, 0x3fb8aa3b, v93
	v_mul_f32_e32 v94, 0x3fb8aa3b, v94
	v_mul_f32_e32 v95, 0x3fb8aa3b, v95
	v_exp_f32_e32 v88, v88
	v_exp_f32_e32 v89, v89
	v_exp_f32_e32 v90, v90
	v_exp_f32_e32 v91, v91
	v_exp_f32_e32 v92, v92
	v_exp_f32_e32 v93, v93
	v_exp_f32_e32 v94, v94
	v_exp_f32_e32 v95, v95
	v_add_f32_e32 v96, v96, v130
	v_add_f32_e32 v97, v97, v130
	v_add_f32_e32 v98, v98, v130
	v_add_f32_e32 v99, v99, v130
	v_add_f32_e32 v100, v100, v130
	v_add_f32_e32 v101, v101, v130
	v_add_f32_e32 v102, v102, v130
	v_add_f32_e32 v103, v103, v130
	v_mul_f32_e32 v96, 0xbfb8aa3b, v96
	v_mul_f32_e32 v97, 0xbfb8aa3b, v97
	v_mul_f32_e32 v98, 0xbfb8aa3b, v98
	v_mul_f32_e32 v99, 0xbfb8aa3b, v99
	v_mul_f32_e32 v100, 0xbfb8aa3b, v100
	v_mul_f32_e32 v101, 0xbfb8aa3b, v101
	v_mul_f32_e32 v102, 0xbfb8aa3b, v102
	v_mul_f32_e32 v103, 0xbfb8aa3b, v103
	v_exp_f32_e32 v96, v96
	v_exp_f32_e32 v97, v97
	v_exp_f32_e32 v98, v98
	v_exp_f32_e32 v99, v99
	v_exp_f32_e32 v100, v100
	v_exp_f32_e32 v101, v101
	v_exp_f32_e32 v102, v102
	v_exp_f32_e32 v103, v103
	v_add_f32_e32 v96, 1.0, v96
	v_add_f32_e32 v97, 1.0, v97
	v_add_f32_e32 v98, 1.0, v98
	v_add_f32_e32 v99, 1.0, v99
	v_add_f32_e32 v100, 1.0, v100
	v_add_f32_e32 v101, 1.0, v101
	v_add_f32_e32 v102, 1.0, v102
	v_add_f32_e32 v103, 1.0, v103
	v_rcp_f32_e32 v96, v96
	v_rcp_f32_e32 v97, v97
	v_rcp_f32_e32 v98, v98
	v_rcp_f32_e32 v99, v99
	v_rcp_f32_e32 v100, v100
	v_rcp_f32_e32 v101, v101
	v_rcp_f32_e32 v102, v102
	v_rcp_f32_e32 v103, v103
	v_mul_f32_e32 v96, 0x41000000, v96
	v_mul_f32_e32 v97, 0x41000000, v97
	v_mul_f32_e32 v98, 0x41000000, v98
	v_mul_f32_e32 v99, 0x41000000, v99
	v_mul_f32_e32 v100, 0x41000000, v100
	v_mul_f32_e32 v101, 0x41000000, v101
	v_mul_f32_e32 v102, 0x41000000, v102
	v_mul_f32_e32 v103, 0x41000000, v103
	v_mul_f32_e32 v96, v96, v134
	v_mul_f32_e32 v97, v97, v134
	v_mul_f32_e32 v98, v98, v134
	v_mul_f32_e32 v99, v99, v134
	v_mul_f32_e32 v100, v100, v134
	v_mul_f32_e32 v101, v101, v134
	v_mul_f32_e32 v102, v102, v134
	v_mul_f32_e32 v103, v103, v134
	v_mul_f32_e32 v96, 0x3fb8aa3b, v96
	v_mul_f32_e32 v97, 0x3fb8aa3b, v97
	v_mul_f32_e32 v98, 0x3fb8aa3b, v98
	v_mul_f32_e32 v99, 0x3fb8aa3b, v99
	v_mul_f32_e32 v100, 0x3fb8aa3b, v100
	v_mul_f32_e32 v101, 0x3fb8aa3b, v101
	v_mul_f32_e32 v102, 0x3fb8aa3b, v102
	v_mul_f32_e32 v103, 0x3fb8aa3b, v103
	v_exp_f32_e32 v96, v96
	v_exp_f32_e32 v97, v97
	v_exp_f32_e32 v98, v98
	v_exp_f32_e32 v99, v99
	v_exp_f32_e32 v100, v100
	v_exp_f32_e32 v101, v101
	v_exp_f32_e32 v102, v102
	v_exp_f32_e32 v103, v103
	v_add_f32_e32 v104, v104, v130
	v_add_f32_e32 v105, v105, v130
	v_add_f32_e32 v106, v106, v130
	v_add_f32_e32 v107, v107, v130
	v_add_f32_e32 v108, v108, v130
	v_add_f32_e32 v109, v109, v130
	v_add_f32_e32 v110, v110, v130
	v_add_f32_e32 v111, v111, v130
	v_mul_f32_e32 v104, 0xbfb8aa3b, v104
	v_mul_f32_e32 v105, 0xbfb8aa3b, v105
	v_mul_f32_e32 v106, 0xbfb8aa3b, v106
	v_mul_f32_e32 v107, 0xbfb8aa3b, v107
	v_mul_f32_e32 v108, 0xbfb8aa3b, v108
	v_mul_f32_e32 v109, 0xbfb8aa3b, v109
	v_mul_f32_e32 v110, 0xbfb8aa3b, v110
	v_mul_f32_e32 v111, 0xbfb8aa3b, v111
	v_exp_f32_e32 v104, v104
	v_exp_f32_e32 v105, v105
	v_exp_f32_e32 v106, v106
	v_exp_f32_e32 v107, v107
	v_exp_f32_e32 v108, v108
	v_exp_f32_e32 v109, v109
	v_exp_f32_e32 v110, v110
	v_exp_f32_e32 v111, v111
	v_add_f32_e32 v104, 1.0, v104
	v_add_f32_e32 v105, 1.0, v105
	v_add_f32_e32 v106, 1.0, v106
	v_add_f32_e32 v107, 1.0, v107
	v_add_f32_e32 v108, 1.0, v108
	v_add_f32_e32 v109, 1.0, v109
	v_add_f32_e32 v110, 1.0, v110
	v_add_f32_e32 v111, 1.0, v111
	v_rcp_f32_e32 v104, v104
	v_rcp_f32_e32 v105, v105
	v_rcp_f32_e32 v106, v106
	v_rcp_f32_e32 v107, v107
	v_rcp_f32_e32 v108, v108
	v_rcp_f32_e32 v109, v109
	v_rcp_f32_e32 v110, v110
	v_rcp_f32_e32 v111, v111
	v_mul_f32_e32 v104, 0x41000000, v104
	v_mul_f32_e32 v105, 0x41000000, v105
	v_mul_f32_e32 v106, 0x41000000, v106
	v_mul_f32_e32 v107, 0x41000000, v107
	v_mul_f32_e32 v108, 0x41000000, v108
	v_mul_f32_e32 v109, 0x41000000, v109
	v_mul_f32_e32 v110, 0x41000000, v110
	v_mul_f32_e32 v111, 0x41000000, v111
	v_mul_f32_e32 v104, v104, v134
	v_mul_f32_e32 v105, v105, v134
	v_mul_f32_e32 v106, v106, v134
	v_mul_f32_e32 v107, v107, v134
	v_mul_f32_e32 v108, v108, v134
	v_mul_f32_e32 v109, v109, v134
	v_mul_f32_e32 v110, v110, v134
	v_mul_f32_e32 v111, v111, v134
	v_mul_f32_e32 v104, 0x3fb8aa3b, v104
	v_mul_f32_e32 v105, 0x3fb8aa3b, v105
	v_mul_f32_e32 v106, 0x3fb8aa3b, v106
	v_mul_f32_e32 v107, 0x3fb8aa3b, v107
	v_mul_f32_e32 v108, 0x3fb8aa3b, v108
	v_mul_f32_e32 v109, 0x3fb8aa3b, v109
	v_mul_f32_e32 v110, 0x3fb8aa3b, v110
	v_mul_f32_e32 v111, 0x3fb8aa3b, v111
	v_exp_f32_e32 v104, v104
	v_exp_f32_e32 v105, v105
	v_exp_f32_e32 v106, v106
	v_exp_f32_e32 v107, v107
	v_exp_f32_e32 v108, v108
	v_exp_f32_e32 v109, v109
	v_exp_f32_e32 v110, v110
	v_exp_f32_e32 v111, v111
	v_add_f32_e32 v112, v112, v131
	v_add_f32_e32 v113, v113, v131
	v_add_f32_e32 v114, v114, v131
	v_add_f32_e32 v115, v115, v131
	v_add_f32_e32 v116, v116, v131
	v_add_f32_e32 v117, v117, v131
	v_add_f32_e32 v118, v118, v131
	v_add_f32_e32 v119, v119, v131
	v_mul_f32_e32 v112, 0xbfb8aa3b, v112
	v_mul_f32_e32 v113, 0xbfb8aa3b, v113
	v_mul_f32_e32 v114, 0xbfb8aa3b, v114
	v_mul_f32_e32 v115, 0xbfb8aa3b, v115
	v_mul_f32_e32 v116, 0xbfb8aa3b, v116
	v_mul_f32_e32 v117, 0xbfb8aa3b, v117
	v_mul_f32_e32 v118, 0xbfb8aa3b, v118
	v_mul_f32_e32 v119, 0xbfb8aa3b, v119
	v_exp_f32_e32 v112, v112
	v_exp_f32_e32 v113, v113
	v_exp_f32_e32 v114, v114
	v_exp_f32_e32 v115, v115
	v_exp_f32_e32 v116, v116
	v_exp_f32_e32 v117, v117
	v_exp_f32_e32 v118, v118
	v_exp_f32_e32 v119, v119
	v_add_f32_e32 v112, 1.0, v112
	v_add_f32_e32 v113, 1.0, v113
	v_add_f32_e32 v114, 1.0, v114
	v_add_f32_e32 v115, 1.0, v115
	v_add_f32_e32 v116, 1.0, v116
	v_add_f32_e32 v117, 1.0, v117
	v_add_f32_e32 v118, 1.0, v118
	v_add_f32_e32 v119, 1.0, v119
	v_rcp_f32_e32 v112, v112
	v_rcp_f32_e32 v113, v113
	v_rcp_f32_e32 v114, v114
	v_rcp_f32_e32 v115, v115
	v_rcp_f32_e32 v116, v116
	v_rcp_f32_e32 v117, v117
	v_rcp_f32_e32 v118, v118
	v_rcp_f32_e32 v119, v119
	v_mul_f32_e32 v112, 0x41000000, v112
	v_mul_f32_e32 v113, 0x41000000, v113
	v_mul_f32_e32 v114, 0x41000000, v114
	v_mul_f32_e32 v115, 0x41000000, v115
	v_mul_f32_e32 v116, 0x41000000, v116
	v_mul_f32_e32 v117, 0x41000000, v117
	v_mul_f32_e32 v118, 0x41000000, v118
	v_mul_f32_e32 v119, 0x41000000, v119
	v_mul_f32_e32 v112, v112, v135
	v_mul_f32_e32 v113, v113, v135
	v_mul_f32_e32 v114, v114, v135
	v_mul_f32_e32 v115, v115, v135
	v_mul_f32_e32 v116, v116, v135
	v_mul_f32_e32 v117, v117, v135
	v_mul_f32_e32 v118, v118, v135
	v_mul_f32_e32 v119, v119, v135
	v_mul_f32_e32 v112, 0x3fb8aa3b, v112
	v_mul_f32_e32 v113, 0x3fb8aa3b, v113
	v_mul_f32_e32 v114, 0x3fb8aa3b, v114
	v_mul_f32_e32 v115, 0x3fb8aa3b, v115
	v_mul_f32_e32 v116, 0x3fb8aa3b, v116
	v_mul_f32_e32 v117, 0x3fb8aa3b, v117
	v_mul_f32_e32 v118, 0x3fb8aa3b, v118
	v_mul_f32_e32 v119, 0x3fb8aa3b, v119
	v_exp_f32_e32 v112, v112
	v_exp_f32_e32 v113, v113
	v_exp_f32_e32 v114, v114
	v_exp_f32_e32 v115, v115
	v_exp_f32_e32 v116, v116
	v_exp_f32_e32 v117, v117
	v_exp_f32_e32 v118, v118
	v_exp_f32_e32 v119, v119
	v_add_f32_e32 v120, v120, v131
	v_add_f32_e32 v121, v121, v131
	v_add_f32_e32 v122, v122, v131
	v_add_f32_e32 v123, v123, v131
	v_add_f32_e32 v124, v124, v131
	v_add_f32_e32 v125, v125, v131
	v_add_f32_e32 v126, v126, v131
	v_add_f32_e32 v127, v127, v131
	v_mul_f32_e32 v120, 0xbfb8aa3b, v120
	v_mul_f32_e32 v121, 0xbfb8aa3b, v121
	v_mul_f32_e32 v122, 0xbfb8aa3b, v122
	v_mul_f32_e32 v123, 0xbfb8aa3b, v123
	v_mul_f32_e32 v124, 0xbfb8aa3b, v124
	v_mul_f32_e32 v125, 0xbfb8aa3b, v125
	v_mul_f32_e32 v126, 0xbfb8aa3b, v126
	v_mul_f32_e32 v127, 0xbfb8aa3b, v127
	v_exp_f32_e32 v120, v120
	v_exp_f32_e32 v121, v121
	v_exp_f32_e32 v122, v122
	v_exp_f32_e32 v123, v123
	v_exp_f32_e32 v124, v124
	v_exp_f32_e32 v125, v125
	v_exp_f32_e32 v126, v126
	v_exp_f32_e32 v127, v127
	v_add_f32_e32 v120, 1.0, v120
	v_add_f32_e32 v121, 1.0, v121
	v_add_f32_e32 v122, 1.0, v122
	v_add_f32_e32 v123, 1.0, v123
	v_add_f32_e32 v124, 1.0, v124
	v_add_f32_e32 v125, 1.0, v125
	v_add_f32_e32 v126, 1.0, v126
	v_add_f32_e32 v127, 1.0, v127
	v_rcp_f32_e32 v120, v120
	v_rcp_f32_e32 v121, v121
	v_rcp_f32_e32 v122, v122
	v_rcp_f32_e32 v123, v123
	v_rcp_f32_e32 v124, v124
	v_rcp_f32_e32 v125, v125
	v_rcp_f32_e32 v126, v126
	v_rcp_f32_e32 v127, v127
	v_mul_f32_e32 v120, 0x41000000, v120
	v_mul_f32_e32 v121, 0x41000000, v121
	v_mul_f32_e32 v122, 0x41000000, v122
	v_mul_f32_e32 v123, 0x41000000, v123
	v_mul_f32_e32 v124, 0x41000000, v124
	v_mul_f32_e32 v125, 0x41000000, v125
	v_mul_f32_e32 v126, 0x41000000, v126
	v_mul_f32_e32 v127, 0x41000000, v127
	v_mul_f32_e32 v120, v120, v135
	v_mul_f32_e32 v121, v121, v135
	v_mul_f32_e32 v122, v122, v135
	v_mul_f32_e32 v123, v123, v135
	v_mul_f32_e32 v124, v124, v135
	v_mul_f32_e32 v125, v125, v135
	v_mul_f32_e32 v126, v126, v135
	v_mul_f32_e32 v127, v127, v135
	v_mul_f32_e32 v120, 0x3fb8aa3b, v120
	v_mul_f32_e32 v121, 0x3fb8aa3b, v121
	v_mul_f32_e32 v122, 0x3fb8aa3b, v122
	v_mul_f32_e32 v123, 0x3fb8aa3b, v123
	v_mul_f32_e32 v124, 0x3fb8aa3b, v124
	v_mul_f32_e32 v125, 0x3fb8aa3b, v125
	v_mul_f32_e32 v126, 0x3fb8aa3b, v126
	v_mul_f32_e32 v127, 0x3fb8aa3b, v127
	v_exp_f32_e32 v120, v120
	v_exp_f32_e32 v121, v121
	v_exp_f32_e32 v122, v122
	v_exp_f32_e32 v123, v123
	v_exp_f32_e32 v124, v124
	v_exp_f32_e32 v125, v125
	v_exp_f32_e32 v126, v126
	v_exp_f32_e32 v127, v127
	ds_read_u16 v0, v147 offset:64
	ds_read_u16 v1, v147 offset:1104
	ds_read_u16 v2, v147 offset:2144
	ds_read_u16 v3, v147 offset:3184
	ds_read_u16 v4, v147 offset:4224
	ds_read_u16 v5, v147 offset:5264
	ds_read_u16 v6, v147 offset:6304
	ds_read_u16 v7, v147 offset:7344
	ds_read_u16 v8, v147 offset:8384
	ds_read_u16 v9, v147 offset:9424
	ds_read_u16 v10, v147 offset:10464
	ds_read_u16 v11, v147 offset:11504
	ds_read_u16 v12, v147 offset:12544
	ds_read_u16 v13, v147 offset:13584
	ds_read_u16 v14, v147 offset:14624
	ds_read_u16 v15, v147 offset:15664
	ds_read_u16 v16, v147 offset:96
	ds_read_u16 v17, v147 offset:1136
	ds_read_u16 v18, v147 offset:2176
	ds_read_u16 v19, v147 offset:3216
	ds_read_u16 v20, v147 offset:4256
	ds_read_u16 v21, v147 offset:5296
	ds_read_u16 v22, v147 offset:6336
	ds_read_u16 v23, v147 offset:7376
	ds_read_u16 v24, v147 offset:8416
	ds_read_u16 v25, v147 offset:9456
	ds_read_u16 v26, v147 offset:10496
	ds_read_u16 v27, v147 offset:11536
	ds_read_u16 v28, v147 offset:12576
	ds_read_u16 v29, v147 offset:13616
	ds_read_u16 v30, v147 offset:14656
	ds_read_u16 v31, v147 offset:15696
	s_waitcnt lgkmcnt(0)
	v_lshlrev_b32_e32 v32, 16, v32
	v_lshlrev_b32_e32 v33, 16, v33
	v_lshlrev_b32_e32 v34, 16, v34
	v_lshlrev_b32_e32 v35, 16, v35
	v_lshlrev_b32_e32 v36, 16, v36
	v_lshlrev_b32_e32 v37, 16, v37
	v_lshlrev_b32_e32 v38, 16, v38
	v_lshlrev_b32_e32 v39, 16, v39
	v_lshlrev_b32_e32 v40, 16, v40
	v_lshlrev_b32_e32 v41, 16, v41
	v_lshlrev_b32_e32 v42, 16, v42
	v_lshlrev_b32_e32 v43, 16, v43
	v_lshlrev_b32_e32 v44, 16, v44
	v_lshlrev_b32_e32 v45, 16, v45
	v_lshlrev_b32_e32 v46, 16, v46
	v_lshlrev_b32_e32 v47, 16, v47
	v_lshlrev_b32_e32 v52, 16, v52
	v_lshlrev_b32_e32 v53, 16, v53
	v_lshlrev_b32_e32 v54, 16, v54
	v_lshlrev_b32_e32 v55, 16, v55
	v_lshlrev_b32_e32 v56, 16, v56
	v_lshlrev_b32_e32 v57, 16, v57
	v_lshlrev_b32_e32 v58, 16, v58
	v_lshlrev_b32_e32 v59, 16, v59
	v_lshlrev_b32_e32 v60, 16, v60
	v_lshlrev_b32_e32 v61, 16, v61
	v_lshlrev_b32_e32 v62, 16, v62
	v_lshlrev_b32_e32 v63, 16, v63
	v_lshlrev_b32_e32 v252, 16, v252
	v_lshlrev_b32_e32 v253, 16, v253
	v_lshlrev_b32_e32 v254, 16, v254
	v_lshlrev_b32_e32 v255, 16, v255
	v_lshlrev_b32_e32 v0, 16, v0
	v_lshlrev_b32_e32 v1, 16, v1
	v_lshlrev_b32_e32 v2, 16, v2
	v_lshlrev_b32_e32 v3, 16, v3
	v_lshlrev_b32_e32 v4, 16, v4
	v_lshlrev_b32_e32 v5, 16, v5
	v_lshlrev_b32_e32 v6, 16, v6
	v_lshlrev_b32_e32 v7, 16, v7
	v_lshlrev_b32_e32 v8, 16, v8
	v_lshlrev_b32_e32 v9, 16, v9
	v_lshlrev_b32_e32 v10, 16, v10
	v_lshlrev_b32_e32 v11, 16, v11
	v_lshlrev_b32_e32 v12, 16, v12
	v_lshlrev_b32_e32 v13, 16, v13
	v_lshlrev_b32_e32 v14, 16, v14
	v_lshlrev_b32_e32 v15, 16, v15
	v_lshlrev_b32_e32 v16, 16, v16
	v_lshlrev_b32_e32 v17, 16, v17
	v_lshlrev_b32_e32 v18, 16, v18
	v_lshlrev_b32_e32 v19, 16, v19
	v_lshlrev_b32_e32 v20, 16, v20
	v_lshlrev_b32_e32 v21, 16, v21
	v_lshlrev_b32_e32 v22, 16, v22
	v_lshlrev_b32_e32 v23, 16, v23
	v_lshlrev_b32_e32 v24, 16, v24
	v_lshlrev_b32_e32 v25, 16, v25
	v_lshlrev_b32_e32 v26, 16, v26
	v_lshlrev_b32_e32 v27, 16, v27
	v_lshlrev_b32_e32 v28, 16, v28
	v_lshlrev_b32_e32 v29, 16, v29
	v_lshlrev_b32_e32 v30, 16, v30
	v_lshlrev_b32_e32 v31, 16, v31
	v_add_f32_e32 v156, v156, v136
	v_add_f32_e32 v157, v157, v136
	v_add_f32_e32 v158, v158, v136
	v_add_f32_e32 v159, v159, v136
	v_mul_f32_e32 v156, 0xbfb8aa3b, v156
	v_mul_f32_e32 v157, 0xbfb8aa3b, v157
	v_mul_f32_e32 v158, 0xbfb8aa3b, v158
	v_mul_f32_e32 v159, 0xbfb8aa3b, v159
	v_exp_f32_e32 v156, v156
	v_exp_f32_e32 v157, v157
	v_exp_f32_e32 v158, v158
	v_exp_f32_e32 v159, v159
	v_fma_f32 v148, -v64, v64, 1.0
	v_fma_f32 v149, -v65, v65, 1.0
	v_fma_f32 v150, -v66, v66, 1.0
	v_fma_f32 v151, -v67, v67, 1.0
	v_add_f32_e32 v156, 1.0, v156
	v_add_f32_e32 v157, 1.0, v157
	v_add_f32_e32 v158, 1.0, v158
	v_add_f32_e32 v159, 1.0, v159
	v_rcp_f32_e32 v156, v156
	v_rcp_f32_e32 v157, v157
	v_rcp_f32_e32 v158, v158
	v_rcp_f32_e32 v159, v159
	v_max_f32_e32 v148, 0, v148
	v_max_f32_e32 v149, 0, v149
	v_max_f32_e32 v150, 0, v150
	v_max_f32_e32 v151, 0, v151
	v_sqrt_f32_e32 v148, v148
	v_sqrt_f32_e32 v149, v149
	v_sqrt_f32_e32 v150, v150
	v_sqrt_f32_e32 v151, v151
	v_mul_f32_e32 v156, v156, v32
	v_mul_f32_e32 v157, v157, v33
	v_mul_f32_e32 v158, v158, v34
	v_mul_f32_e32 v159, v159, v35
	v_mul_f32_e32 v156, v156, v148
	v_mul_f32_e32 v157, v157, v149
	v_mul_f32_e32 v158, v158, v150
	v_mul_f32_e32 v159, v159, v151
	v_add_f32_e32 v160, v160, v136
	v_add_f32_e32 v161, v161, v136
	v_add_f32_e32 v162, v162, v136
	v_add_f32_e32 v163, v163, v136
	v_mul_f32_e32 v160, 0xbfb8aa3b, v160
	v_mul_f32_e32 v161, 0xbfb8aa3b, v161
	v_mul_f32_e32 v162, 0xbfb8aa3b, v162
	v_mul_f32_e32 v163, 0xbfb8aa3b, v163
	v_exp_f32_e32 v160, v160
	v_exp_f32_e32 v161, v161
	v_exp_f32_e32 v162, v162
	v_exp_f32_e32 v163, v163
	v_fma_f32 v148, -v68, v68, 1.0
	v_fma_f32 v149, -v69, v69, 1.0
	v_fma_f32 v150, -v70, v70, 1.0
	v_fma_f32 v151, -v71, v71, 1.0
	v_add_f32_e32 v160, 1.0, v160
	v_add_f32_e32 v161, 1.0, v161
	v_add_f32_e32 v162, 1.0, v162
	v_add_f32_e32 v163, 1.0, v163
	v_rcp_f32_e32 v160, v160
	v_rcp_f32_e32 v161, v161
	v_rcp_f32_e32 v162, v162
	v_rcp_f32_e32 v163, v163
	v_max_f32_e32 v148, 0, v148
	v_max_f32_e32 v149, 0, v149
	v_max_f32_e32 v150, 0, v150
	v_max_f32_e32 v151, 0, v151
	v_sqrt_f32_e32 v148, v148
	v_sqrt_f32_e32 v149, v149
	v_sqrt_f32_e32 v150, v150
	v_sqrt_f32_e32 v151, v151
	v_mul_f32_e32 v160, v160, v36
	v_mul_f32_e32 v161, v161, v37
	v_mul_f32_e32 v162, v162, v38
	v_mul_f32_e32 v163, v163, v39
	v_mul_f32_e32 v160, v160, v148
	v_mul_f32_e32 v161, v161, v149
	v_mul_f32_e32 v162, v162, v150
	v_mul_f32_e32 v163, v163, v151
	v_add_f32_e32 v164, v164, v136
	v_add_f32_e32 v165, v165, v136
	v_add_f32_e32 v166, v166, v136
	v_add_f32_e32 v167, v167, v136
	v_mul_f32_e32 v164, 0xbfb8aa3b, v164
	v_mul_f32_e32 v165, 0xbfb8aa3b, v165
	v_mul_f32_e32 v166, 0xbfb8aa3b, v166
	v_mul_f32_e32 v167, 0xbfb8aa3b, v167
	v_exp_f32_e32 v164, v164
	v_exp_f32_e32 v165, v165
	v_exp_f32_e32 v166, v166
	v_exp_f32_e32 v167, v167
	v_fma_f32 v148, -v72, v72, 1.0
	v_fma_f32 v149, -v73, v73, 1.0
	v_fma_f32 v150, -v74, v74, 1.0
	v_fma_f32 v151, -v75, v75, 1.0
	v_add_f32_e32 v164, 1.0, v164
	v_add_f32_e32 v165, 1.0, v165
	v_add_f32_e32 v166, 1.0, v166
	v_add_f32_e32 v167, 1.0, v167
	v_rcp_f32_e32 v164, v164
	v_rcp_f32_e32 v165, v165
	v_rcp_f32_e32 v166, v166
	v_rcp_f32_e32 v167, v167
	v_max_f32_e32 v148, 0, v148
	v_max_f32_e32 v149, 0, v149
	v_max_f32_e32 v150, 0, v150
	v_max_f32_e32 v151, 0, v151
	v_sqrt_f32_e32 v148, v148
	v_sqrt_f32_e32 v149, v149
	v_sqrt_f32_e32 v150, v150
	v_sqrt_f32_e32 v151, v151
	v_mul_f32_e32 v164, v164, v40
	v_mul_f32_e32 v165, v165, v41
	v_mul_f32_e32 v166, v166, v42
	v_mul_f32_e32 v167, v167, v43
	v_mul_f32_e32 v164, v164, v148
	v_mul_f32_e32 v165, v165, v149
	v_mul_f32_e32 v166, v166, v150
	v_mul_f32_e32 v167, v167, v151
	v_add_f32_e32 v168, v168, v136
	v_add_f32_e32 v169, v169, v136
	v_add_f32_e32 v170, v170, v136
	v_add_f32_e32 v171, v171, v136
	v_mul_f32_e32 v168, 0xbfb8aa3b, v168
	v_mul_f32_e32 v169, 0xbfb8aa3b, v169
	v_mul_f32_e32 v170, 0xbfb8aa3b, v170
	v_mul_f32_e32 v171, 0xbfb8aa3b, v171
	v_exp_f32_e32 v168, v168
	v_exp_f32_e32 v169, v169
	v_exp_f32_e32 v170, v170
	v_exp_f32_e32 v171, v171
	v_fma_f32 v148, -v76, v76, 1.0
	v_fma_f32 v149, -v77, v77, 1.0
	v_fma_f32 v150, -v78, v78, 1.0
	v_fma_f32 v151, -v79, v79, 1.0
	v_add_f32_e32 v168, 1.0, v168
	v_add_f32_e32 v169, 1.0, v169
	v_add_f32_e32 v170, 1.0, v170
	v_add_f32_e32 v171, 1.0, v171
	v_rcp_f32_e32 v168, v168
	v_rcp_f32_e32 v169, v169
	v_rcp_f32_e32 v170, v170
	v_rcp_f32_e32 v171, v171
	v_max_f32_e32 v148, 0, v148
	v_max_f32_e32 v149, 0, v149
	v_max_f32_e32 v150, 0, v150
	v_max_f32_e32 v151, 0, v151
	v_sqrt_f32_e32 v148, v148
	v_sqrt_f32_e32 v149, v149
	v_sqrt_f32_e32 v150, v150
	v_sqrt_f32_e32 v151, v151
	v_mul_f32_e32 v168, v168, v44
	v_mul_f32_e32 v169, v169, v45
	v_mul_f32_e32 v170, v170, v46
	v_mul_f32_e32 v171, v171, v47
	v_mul_f32_e32 v168, v168, v148
	v_mul_f32_e32 v169, v169, v149
	v_mul_f32_e32 v170, v170, v150
	v_mul_f32_e32 v171, v171, v151
	v_add_f32_e32 v172, v172, v137
	v_add_f32_e32 v173, v173, v137
	v_add_f32_e32 v174, v174, v137
	v_add_f32_e32 v175, v175, v137
	v_mul_f32_e32 v172, 0xbfb8aa3b, v172
	v_mul_f32_e32 v173, 0xbfb8aa3b, v173
	v_mul_f32_e32 v174, 0xbfb8aa3b, v174
	v_mul_f32_e32 v175, 0xbfb8aa3b, v175
	v_exp_f32_e32 v172, v172
	v_exp_f32_e32 v173, v173
	v_exp_f32_e32 v174, v174
	v_exp_f32_e32 v175, v175
	v_fma_f32 v148, -v80, v80, 1.0
	v_fma_f32 v149, -v81, v81, 1.0
	v_fma_f32 v150, -v82, v82, 1.0
	v_fma_f32 v151, -v83, v83, 1.0
	v_add_f32_e32 v172, 1.0, v172
	v_add_f32_e32 v173, 1.0, v173
	v_add_f32_e32 v174, 1.0, v174
	v_add_f32_e32 v175, 1.0, v175
	v_rcp_f32_e32 v172, v172
	v_rcp_f32_e32 v173, v173
	v_rcp_f32_e32 v174, v174
	v_rcp_f32_e32 v175, v175
	v_max_f32_e32 v148, 0, v148
	v_max_f32_e32 v149, 0, v149
	v_max_f32_e32 v150, 0, v150
	v_max_f32_e32 v151, 0, v151
	v_sqrt_f32_e32 v148, v148
	v_sqrt_f32_e32 v149, v149
	v_sqrt_f32_e32 v150, v150
	v_sqrt_f32_e32 v151, v151
	v_mul_f32_e32 v172, v172, v52
	v_mul_f32_e32 v173, v173, v53
	v_mul_f32_e32 v174, v174, v54
	v_mul_f32_e32 v175, v175, v55
	v_mul_f32_e32 v172, v172, v148
	v_mul_f32_e32 v173, v173, v149
	v_mul_f32_e32 v174, v174, v150
	v_mul_f32_e32 v175, v175, v151
	v_add_f32_e32 v176, v176, v137
	v_add_f32_e32 v177, v177, v137
	v_add_f32_e32 v178, v178, v137
	v_add_f32_e32 v179, v179, v137
	v_mul_f32_e32 v176, 0xbfb8aa3b, v176
	v_mul_f32_e32 v177, 0xbfb8aa3b, v177
	v_mul_f32_e32 v178, 0xbfb8aa3b, v178
	v_mul_f32_e32 v179, 0xbfb8aa3b, v179
	v_exp_f32_e32 v176, v176
	v_exp_f32_e32 v177, v177
	v_exp_f32_e32 v178, v178
	v_exp_f32_e32 v179, v179
	v_fma_f32 v148, -v84, v84, 1.0
	v_fma_f32 v149, -v85, v85, 1.0
	v_fma_f32 v150, -v86, v86, 1.0
	v_fma_f32 v151, -v87, v87, 1.0
	v_add_f32_e32 v176, 1.0, v176
	v_add_f32_e32 v177, 1.0, v177
	v_add_f32_e32 v178, 1.0, v178
	v_add_f32_e32 v179, 1.0, v179
	v_rcp_f32_e32 v176, v176
	v_rcp_f32_e32 v177, v177
	v_rcp_f32_e32 v178, v178
	v_rcp_f32_e32 v179, v179
	v_max_f32_e32 v148, 0, v148
	v_max_f32_e32 v149, 0, v149
	v_max_f32_e32 v150, 0, v150
	v_max_f32_e32 v151, 0, v151
	v_sqrt_f32_e32 v148, v148
	v_sqrt_f32_e32 v149, v149
	v_sqrt_f32_e32 v150, v150
	v_sqrt_f32_e32 v151, v151
	v_mul_f32_e32 v176, v176, v56
	v_mul_f32_e32 v177, v177, v57
	v_mul_f32_e32 v178, v178, v58
	v_mul_f32_e32 v179, v179, v59
	v_mul_f32_e32 v176, v176, v148
	v_mul_f32_e32 v177, v177, v149
	v_mul_f32_e32 v178, v178, v150
	v_mul_f32_e32 v179, v179, v151
	v_add_f32_e32 v180, v180, v137
	v_add_f32_e32 v181, v181, v137
	v_add_f32_e32 v182, v182, v137
	v_add_f32_e32 v183, v183, v137
	v_mul_f32_e32 v180, 0xbfb8aa3b, v180
	v_mul_f32_e32 v181, 0xbfb8aa3b, v181
	v_mul_f32_e32 v182, 0xbfb8aa3b, v182
	v_mul_f32_e32 v183, 0xbfb8aa3b, v183
	v_exp_f32_e32 v180, v180
	v_exp_f32_e32 v181, v181
	v_exp_f32_e32 v182, v182
	v_exp_f32_e32 v183, v183
	v_fma_f32 v148, -v88, v88, 1.0
	v_fma_f32 v149, -v89, v89, 1.0
	v_fma_f32 v150, -v90, v90, 1.0
	v_fma_f32 v151, -v91, v91, 1.0
	v_add_f32_e32 v180, 1.0, v180
	v_add_f32_e32 v181, 1.0, v181
	v_add_f32_e32 v182, 1.0, v182
	v_add_f32_e32 v183, 1.0, v183
	v_rcp_f32_e32 v180, v180
	v_rcp_f32_e32 v181, v181
	v_rcp_f32_e32 v182, v182
	v_rcp_f32_e32 v183, v183
	v_max_f32_e32 v148, 0, v148
	v_max_f32_e32 v149, 0, v149
	v_max_f32_e32 v150, 0, v150
	v_max_f32_e32 v151, 0, v151
	v_sqrt_f32_e32 v148, v148
	v_sqrt_f32_e32 v149, v149
	v_sqrt_f32_e32 v150, v150
	v_sqrt_f32_e32 v151, v151
	v_mul_f32_e32 v180, v180, v60
	v_mul_f32_e32 v181, v181, v61
	v_mul_f32_e32 v182, v182, v62
	v_mul_f32_e32 v183, v183, v63
	v_mul_f32_e32 v180, v180, v148
	v_mul_f32_e32 v181, v181, v149
	v_mul_f32_e32 v182, v182, v150
	v_mul_f32_e32 v183, v183, v151
	v_add_f32_e32 v184, v184, v137
	v_add_f32_e32 v185, v185, v137
	v_add_f32_e32 v186, v186, v137
	v_add_f32_e32 v187, v187, v137
	v_mul_f32_e32 v184, 0xbfb8aa3b, v184
	v_mul_f32_e32 v185, 0xbfb8aa3b, v185
	v_mul_f32_e32 v186, 0xbfb8aa3b, v186
	v_mul_f32_e32 v187, 0xbfb8aa3b, v187
	v_exp_f32_e32 v184, v184
	v_exp_f32_e32 v185, v185
	v_exp_f32_e32 v186, v186
	v_exp_f32_e32 v187, v187
	v_fma_f32 v148, -v92, v92, 1.0
	v_fma_f32 v149, -v93, v93, 1.0
	v_fma_f32 v150, -v94, v94, 1.0
	v_fma_f32 v151, -v95, v95, 1.0
	v_add_f32_e32 v184, 1.0, v184
	v_add_f32_e32 v185, 1.0, v185
	v_add_f32_e32 v186, 1.0, v186
	v_add_f32_e32 v187, 1.0, v187
	v_rcp_f32_e32 v184, v184
	v_rcp_f32_e32 v185, v185
	v_rcp_f32_e32 v186, v186
	v_rcp_f32_e32 v187, v187
	v_max_f32_e32 v148, 0, v148
	v_max_f32_e32 v149, 0, v149
	v_max_f32_e32 v150, 0, v150
	v_max_f32_e32 v151, 0, v151
	v_sqrt_f32_e32 v148, v148
	v_sqrt_f32_e32 v149, v149
	v_sqrt_f32_e32 v150, v150
	v_sqrt_f32_e32 v151, v151
	v_mul_f32_e32 v184, v184, v252
	v_mul_f32_e32 v185, v185, v253
	v_mul_f32_e32 v186, v186, v254
	v_mul_f32_e32 v187, v187, v255
	v_mul_f32_e32 v184, v184, v148
	v_mul_f32_e32 v185, v185, v149
	v_mul_f32_e32 v186, v186, v150
	v_mul_f32_e32 v187, v187, v151
	v_add_f32_e32 v188, v188, v138
	v_add_f32_e32 v189, v189, v138
	v_add_f32_e32 v190, v190, v138
	v_add_f32_e32 v191, v191, v138
	v_mul_f32_e32 v188, 0xbfb8aa3b, v188
	v_mul_f32_e32 v189, 0xbfb8aa3b, v189
	v_mul_f32_e32 v190, 0xbfb8aa3b, v190
	v_mul_f32_e32 v191, 0xbfb8aa3b, v191
	v_exp_f32_e32 v188, v188
	v_exp_f32_e32 v189, v189
	v_exp_f32_e32 v190, v190
	v_exp_f32_e32 v191, v191
	v_fma_f32 v148, -v96, v96, 1.0
	v_fma_f32 v149, -v97, v97, 1.0
	v_fma_f32 v150, -v98, v98, 1.0
	v_fma_f32 v151, -v99, v99, 1.0
	v_add_f32_e32 v188, 1.0, v188
	v_add_f32_e32 v189, 1.0, v189
	v_add_f32_e32 v190, 1.0, v190
	v_add_f32_e32 v191, 1.0, v191
	v_rcp_f32_e32 v188, v188
	v_rcp_f32_e32 v189, v189
	v_rcp_f32_e32 v190, v190
	v_rcp_f32_e32 v191, v191
	v_max_f32_e32 v148, 0, v148
	v_max_f32_e32 v149, 0, v149
	v_max_f32_e32 v150, 0, v150
	v_max_f32_e32 v151, 0, v151
	v_sqrt_f32_e32 v148, v148
	v_sqrt_f32_e32 v149, v149
	v_sqrt_f32_e32 v150, v150
	v_sqrt_f32_e32 v151, v151
	v_mul_f32_e32 v188, v188, v0
	v_mul_f32_e32 v189, v189, v1
	v_mul_f32_e32 v190, v190, v2
	v_mul_f32_e32 v191, v191, v3
	v_mul_f32_e32 v188, v188, v148
	v_mul_f32_e32 v189, v189, v149
	v_mul_f32_e32 v190, v190, v150
	v_mul_f32_e32 v191, v191, v151
	v_add_f32_e32 v192, v192, v138
	v_add_f32_e32 v193, v193, v138
	v_add_f32_e32 v194, v194, v138
	v_add_f32_e32 v195, v195, v138
	v_mul_f32_e32 v192, 0xbfb8aa3b, v192
	v_mul_f32_e32 v193, 0xbfb8aa3b, v193
	v_mul_f32_e32 v194, 0xbfb8aa3b, v194
	v_mul_f32_e32 v195, 0xbfb8aa3b, v195
	v_exp_f32_e32 v192, v192
	v_exp_f32_e32 v193, v193
	v_exp_f32_e32 v194, v194
	v_exp_f32_e32 v195, v195
	v_fma_f32 v148, -v100, v100, 1.0
	v_fma_f32 v149, -v101, v101, 1.0
	v_fma_f32 v150, -v102, v102, 1.0
	v_fma_f32 v151, -v103, v103, 1.0
	v_add_f32_e32 v192, 1.0, v192
	v_add_f32_e32 v193, 1.0, v193
	v_add_f32_e32 v194, 1.0, v194
	v_add_f32_e32 v195, 1.0, v195
	v_rcp_f32_e32 v192, v192
	v_rcp_f32_e32 v193, v193
	v_rcp_f32_e32 v194, v194
	v_rcp_f32_e32 v195, v195
	v_max_f32_e32 v148, 0, v148
	v_max_f32_e32 v149, 0, v149
	v_max_f32_e32 v150, 0, v150
	v_max_f32_e32 v151, 0, v151
	v_sqrt_f32_e32 v148, v148
	v_sqrt_f32_e32 v149, v149
	v_sqrt_f32_e32 v150, v150
	v_sqrt_f32_e32 v151, v151
	v_mul_f32_e32 v192, v192, v4
	v_mul_f32_e32 v193, v193, v5
	v_mul_f32_e32 v194, v194, v6
	v_mul_f32_e32 v195, v195, v7
	v_mul_f32_e32 v192, v192, v148
	v_mul_f32_e32 v193, v193, v149
	v_mul_f32_e32 v194, v194, v150
	v_mul_f32_e32 v195, v195, v151
	v_add_f32_e32 v196, v196, v138
	v_add_f32_e32 v197, v197, v138
	v_add_f32_e32 v198, v198, v138
	v_add_f32_e32 v199, v199, v138
	v_mul_f32_e32 v196, 0xbfb8aa3b, v196
	v_mul_f32_e32 v197, 0xbfb8aa3b, v197
	v_mul_f32_e32 v198, 0xbfb8aa3b, v198
	v_mul_f32_e32 v199, 0xbfb8aa3b, v199
	v_exp_f32_e32 v196, v196
	v_exp_f32_e32 v197, v197
	v_exp_f32_e32 v198, v198
	v_exp_f32_e32 v199, v199
	v_fma_f32 v148, -v104, v104, 1.0
	v_fma_f32 v149, -v105, v105, 1.0
	v_fma_f32 v150, -v106, v106, 1.0
	v_fma_f32 v151, -v107, v107, 1.0
	v_add_f32_e32 v196, 1.0, v196
	v_add_f32_e32 v197, 1.0, v197
	v_add_f32_e32 v198, 1.0, v198
	v_add_f32_e32 v199, 1.0, v199
	v_rcp_f32_e32 v196, v196
	v_rcp_f32_e32 v197, v197
	v_rcp_f32_e32 v198, v198
	v_rcp_f32_e32 v199, v199
	v_max_f32_e32 v148, 0, v148
	v_max_f32_e32 v149, 0, v149
	v_max_f32_e32 v150, 0, v150
	v_max_f32_e32 v151, 0, v151
	v_sqrt_f32_e32 v148, v148
	v_sqrt_f32_e32 v149, v149
	v_sqrt_f32_e32 v150, v150
	v_sqrt_f32_e32 v151, v151
	v_mul_f32_e32 v196, v196, v8
	v_mul_f32_e32 v197, v197, v9
	v_mul_f32_e32 v198, v198, v10
	v_mul_f32_e32 v199, v199, v11
	v_mul_f32_e32 v196, v196, v148
	v_mul_f32_e32 v197, v197, v149
	v_mul_f32_e32 v198, v198, v150
	v_mul_f32_e32 v199, v199, v151
	v_add_f32_e32 v200, v200, v138
	v_add_f32_e32 v201, v201, v138
	v_add_f32_e32 v202, v202, v138
	v_add_f32_e32 v203, v203, v138
	v_mul_f32_e32 v200, 0xbfb8aa3b, v200
	v_mul_f32_e32 v201, 0xbfb8aa3b, v201
	v_mul_f32_e32 v202, 0xbfb8aa3b, v202
	v_mul_f32_e32 v203, 0xbfb8aa3b, v203
	v_exp_f32_e32 v200, v200
	v_exp_f32_e32 v201, v201
	v_exp_f32_e32 v202, v202
	v_exp_f32_e32 v203, v203
	v_fma_f32 v148, -v108, v108, 1.0
	v_fma_f32 v149, -v109, v109, 1.0
	v_fma_f32 v150, -v110, v110, 1.0
	v_fma_f32 v151, -v111, v111, 1.0
	v_add_f32_e32 v200, 1.0, v200
	v_add_f32_e32 v201, 1.0, v201
	v_add_f32_e32 v202, 1.0, v202
	v_add_f32_e32 v203, 1.0, v203
	v_rcp_f32_e32 v200, v200
	v_rcp_f32_e32 v201, v201
	v_rcp_f32_e32 v202, v202
	v_rcp_f32_e32 v203, v203
	v_max_f32_e32 v148, 0, v148
	v_max_f32_e32 v149, 0, v149
	v_max_f32_e32 v150, 0, v150
	v_max_f32_e32 v151, 0, v151
	v_sqrt_f32_e32 v148, v148
	v_sqrt_f32_e32 v149, v149
	v_sqrt_f32_e32 v150, v150
	v_sqrt_f32_e32 v151, v151
	v_mul_f32_e32 v200, v200, v12
	v_mul_f32_e32 v201, v201, v13
	v_mul_f32_e32 v202, v202, v14
	v_mul_f32_e32 v203, v203, v15
	v_mul_f32_e32 v200, v200, v148
	v_mul_f32_e32 v201, v201, v149
	v_mul_f32_e32 v202, v202, v150
	v_mul_f32_e32 v203, v203, v151
	v_add_f32_e32 v204, v204, v139
	v_add_f32_e32 v205, v205, v139
	v_add_f32_e32 v206, v206, v139
	v_add_f32_e32 v207, v207, v139
	v_mul_f32_e32 v204, 0xbfb8aa3b, v204
	v_mul_f32_e32 v205, 0xbfb8aa3b, v205
	v_mul_f32_e32 v206, 0xbfb8aa3b, v206
	v_mul_f32_e32 v207, 0xbfb8aa3b, v207
	v_exp_f32_e32 v204, v204
	v_exp_f32_e32 v205, v205
	v_exp_f32_e32 v206, v206
	v_exp_f32_e32 v207, v207
	v_fma_f32 v148, -v112, v112, 1.0
	v_fma_f32 v149, -v113, v113, 1.0
	v_fma_f32 v150, -v114, v114, 1.0
	v_fma_f32 v151, -v115, v115, 1.0
	v_add_f32_e32 v204, 1.0, v204
	v_add_f32_e32 v205, 1.0, v205
	v_add_f32_e32 v206, 1.0, v206
	v_add_f32_e32 v207, 1.0, v207
	v_rcp_f32_e32 v204, v204
	v_rcp_f32_e32 v205, v205
	v_rcp_f32_e32 v206, v206
	v_rcp_f32_e32 v207, v207
	v_max_f32_e32 v148, 0, v148
	v_max_f32_e32 v149, 0, v149
	v_max_f32_e32 v150, 0, v150
	v_max_f32_e32 v151, 0, v151
	v_sqrt_f32_e32 v148, v148
	v_sqrt_f32_e32 v149, v149
	v_sqrt_f32_e32 v150, v150
	v_sqrt_f32_e32 v151, v151
	v_mul_f32_e32 v204, v204, v16
	v_mul_f32_e32 v205, v205, v17
	v_mul_f32_e32 v206, v206, v18
	v_mul_f32_e32 v207, v207, v19
	v_mul_f32_e32 v204, v204, v148
	v_mul_f32_e32 v205, v205, v149
	v_mul_f32_e32 v206, v206, v150
	v_mul_f32_e32 v207, v207, v151
	v_add_f32_e32 v208, v208, v139
	v_add_f32_e32 v209, v209, v139
	v_add_f32_e32 v210, v210, v139
	v_add_f32_e32 v211, v211, v139
	v_mul_f32_e32 v208, 0xbfb8aa3b, v208
	v_mul_f32_e32 v209, 0xbfb8aa3b, v209
	v_mul_f32_e32 v210, 0xbfb8aa3b, v210
	v_mul_f32_e32 v211, 0xbfb8aa3b, v211
	v_exp_f32_e32 v208, v208
	v_exp_f32_e32 v209, v209
	v_exp_f32_e32 v210, v210
	v_exp_f32_e32 v211, v211
	v_fma_f32 v148, -v116, v116, 1.0
	v_fma_f32 v149, -v117, v117, 1.0
	v_fma_f32 v150, -v118, v118, 1.0
	v_fma_f32 v151, -v119, v119, 1.0
	v_add_f32_e32 v208, 1.0, v208
	v_add_f32_e32 v209, 1.0, v209
	v_add_f32_e32 v210, 1.0, v210
	v_add_f32_e32 v211, 1.0, v211
	v_rcp_f32_e32 v208, v208
	v_rcp_f32_e32 v209, v209
	v_rcp_f32_e32 v210, v210
	v_rcp_f32_e32 v211, v211
	v_max_f32_e32 v148, 0, v148
	v_max_f32_e32 v149, 0, v149
	v_max_f32_e32 v150, 0, v150
	v_max_f32_e32 v151, 0, v151
	v_sqrt_f32_e32 v148, v148
	v_sqrt_f32_e32 v149, v149
	v_sqrt_f32_e32 v150, v150
	v_sqrt_f32_e32 v151, v151
	v_mul_f32_e32 v208, v208, v20
	v_mul_f32_e32 v209, v209, v21
	v_mul_f32_e32 v210, v210, v22
	v_mul_f32_e32 v211, v211, v23
	v_mul_f32_e32 v208, v208, v148
	v_mul_f32_e32 v209, v209, v149
	v_mul_f32_e32 v210, v210, v150
	v_mul_f32_e32 v211, v211, v151
	v_add_f32_e32 v212, v212, v139
	v_add_f32_e32 v213, v213, v139
	v_add_f32_e32 v214, v214, v139
	v_add_f32_e32 v215, v215, v139
	v_mul_f32_e32 v212, 0xbfb8aa3b, v212
	v_mul_f32_e32 v213, 0xbfb8aa3b, v213
	v_mul_f32_e32 v214, 0xbfb8aa3b, v214
	v_mul_f32_e32 v215, 0xbfb8aa3b, v215
	v_exp_f32_e32 v212, v212
	v_exp_f32_e32 v213, v213
	v_exp_f32_e32 v214, v214
	v_exp_f32_e32 v215, v215
	v_fma_f32 v148, -v120, v120, 1.0
	v_fma_f32 v149, -v121, v121, 1.0
	v_fma_f32 v150, -v122, v122, 1.0
	v_fma_f32 v151, -v123, v123, 1.0
	v_add_f32_e32 v212, 1.0, v212
	v_add_f32_e32 v213, 1.0, v213
	v_add_f32_e32 v214, 1.0, v214
	v_add_f32_e32 v215, 1.0, v215
	v_rcp_f32_e32 v212, v212
	v_rcp_f32_e32 v213, v213
	v_rcp_f32_e32 v214, v214
	v_rcp_f32_e32 v215, v215
	v_max_f32_e32 v148, 0, v148
	v_max_f32_e32 v149, 0, v149
	v_max_f32_e32 v150, 0, v150
	v_max_f32_e32 v151, 0, v151
	v_sqrt_f32_e32 v148, v148
	v_sqrt_f32_e32 v149, v149
	v_sqrt_f32_e32 v150, v150
	v_sqrt_f32_e32 v151, v151
	v_mul_f32_e32 v212, v212, v24
	v_mul_f32_e32 v213, v213, v25
	v_mul_f32_e32 v214, v214, v26
	v_mul_f32_e32 v215, v215, v27
	v_mul_f32_e32 v212, v212, v148
	v_mul_f32_e32 v213, v213, v149
	v_mul_f32_e32 v214, v214, v150
	v_mul_f32_e32 v215, v215, v151
	v_add_f32_e32 v216, v216, v139
	v_add_f32_e32 v217, v217, v139
	v_add_f32_e32 v218, v218, v139
	v_add_f32_e32 v219, v219, v139
	v_mul_f32_e32 v216, 0xbfb8aa3b, v216
	v_mul_f32_e32 v217, 0xbfb8aa3b, v217
	v_mul_f32_e32 v218, 0xbfb8aa3b, v218
	v_mul_f32_e32 v219, 0xbfb8aa3b, v219
	v_exp_f32_e32 v216, v216
	v_exp_f32_e32 v217, v217
	v_exp_f32_e32 v218, v218
	v_exp_f32_e32 v219, v219
	v_fma_f32 v148, -v124, v124, 1.0
	v_fma_f32 v149, -v125, v125, 1.0
	v_fma_f32 v150, -v126, v126, 1.0
	v_fma_f32 v151, -v127, v127, 1.0
	v_add_f32_e32 v216, 1.0, v216
	v_add_f32_e32 v217, 1.0, v217
	v_add_f32_e32 v218, 1.0, v218
	v_add_f32_e32 v219, 1.0, v219
	v_rcp_f32_e32 v216, v216
	v_rcp_f32_e32 v217, v217
	v_rcp_f32_e32 v218, v218
	v_rcp_f32_e32 v219, v219
	v_max_f32_e32 v148, 0, v148
	v_max_f32_e32 v149, 0, v149
	v_max_f32_e32 v150, 0, v150
	v_max_f32_e32 v151, 0, v151
	v_sqrt_f32_e32 v148, v148
	v_sqrt_f32_e32 v149, v149
	v_sqrt_f32_e32 v150, v150
	v_sqrt_f32_e32 v151, v151
	v_mul_f32_e32 v216, v216, v28
	v_mul_f32_e32 v217, v217, v29
	v_mul_f32_e32 v218, v218, v30
	v_mul_f32_e32 v219, v219, v31
	v_mul_f32_e32 v216, v216, v148
	v_mul_f32_e32 v217, v217, v149
	v_mul_f32_e32 v218, v218, v150
	v_mul_f32_e32 v219, v219, v151
	v_fmac_f32_e32 v157, v65, v156
	v_fmac_f32_e32 v173, v81, v172
	v_fmac_f32_e32 v189, v97, v188
	v_fmac_f32_e32 v205, v113, v204
	v_mul_f32_e32 v65, v64, v65
	v_mul_f32_e32 v81, v80, v81
	v_mul_f32_e32 v97, v96, v97
	v_mul_f32_e32 v113, v112, v113
	v_fmac_f32_e32 v158, v66, v157
	v_fmac_f32_e32 v174, v82, v173
	v_fmac_f32_e32 v190, v98, v189
	v_fmac_f32_e32 v206, v114, v205
	v_mul_f32_e32 v66, v65, v66
	v_mul_f32_e32 v82, v81, v82
	v_mul_f32_e32 v98, v97, v98
	v_mul_f32_e32 v114, v113, v114
	v_fmac_f32_e32 v159, v67, v158
	v_fmac_f32_e32 v175, v83, v174
	v_fmac_f32_e32 v191, v99, v190
	v_fmac_f32_e32 v207, v115, v206
	v_mul_f32_e32 v67, v66, v67
	v_mul_f32_e32 v83, v82, v83
	v_mul_f32_e32 v99, v98, v99
	v_mul_f32_e32 v115, v114, v115
	v_fmac_f32_e32 v160, v68, v159
	v_fmac_f32_e32 v176, v84, v175
	v_fmac_f32_e32 v192, v100, v191
	v_fmac_f32_e32 v208, v116, v207
	v_mul_f32_e32 v68, v67, v68
	v_mul_f32_e32 v84, v83, v84
	v_mul_f32_e32 v100, v99, v100
	v_mul_f32_e32 v116, v115, v116
	v_fmac_f32_e32 v161, v69, v160
	v_fmac_f32_e32 v177, v85, v176
	v_fmac_f32_e32 v193, v101, v192
	v_fmac_f32_e32 v209, v117, v208
	v_mul_f32_e32 v69, v68, v69
	v_mul_f32_e32 v85, v84, v85
	v_mul_f32_e32 v101, v100, v101
	v_mul_f32_e32 v117, v116, v117
	v_fmac_f32_e32 v162, v70, v161
	v_fmac_f32_e32 v178, v86, v177
	v_fmac_f32_e32 v194, v102, v193
	v_fmac_f32_e32 v210, v118, v209
	v_mul_f32_e32 v70, v69, v70
	v_mul_f32_e32 v86, v85, v86
	v_mul_f32_e32 v102, v101, v102
	v_mul_f32_e32 v118, v117, v118
	v_fmac_f32_e32 v163, v71, v162
	v_fmac_f32_e32 v179, v87, v178
	v_fmac_f32_e32 v195, v103, v194
	v_fmac_f32_e32 v211, v119, v210
	v_mul_f32_e32 v71, v70, v71
	v_mul_f32_e32 v87, v86, v87
	v_mul_f32_e32 v103, v102, v103
	v_mul_f32_e32 v119, v118, v119
	v_fmac_f32_e32 v164, v72, v163
	v_fmac_f32_e32 v180, v88, v179
	v_fmac_f32_e32 v196, v104, v195
	v_fmac_f32_e32 v212, v120, v211
	v_mul_f32_e32 v72, v71, v72
	v_mul_f32_e32 v88, v87, v88
	v_mul_f32_e32 v104, v103, v104
	v_mul_f32_e32 v120, v119, v120
	v_fmac_f32_e32 v165, v73, v164
	v_fmac_f32_e32 v181, v89, v180
	v_fmac_f32_e32 v197, v105, v196
	v_fmac_f32_e32 v213, v121, v212
	v_mul_f32_e32 v73, v72, v73
	v_mul_f32_e32 v89, v88, v89
	v_mul_f32_e32 v105, v104, v105
	v_mul_f32_e32 v121, v120, v121
	v_fmac_f32_e32 v166, v74, v165
	v_fmac_f32_e32 v182, v90, v181
	v_fmac_f32_e32 v198, v106, v197
	v_fmac_f32_e32 v214, v122, v213
	v_mul_f32_e32 v74, v73, v74
	v_mul_f32_e32 v90, v89, v90
	v_mul_f32_e32 v106, v105, v106
	v_mul_f32_e32 v122, v121, v122
	v_fmac_f32_e32 v167, v75, v166
	v_fmac_f32_e32 v183, v91, v182
	v_fmac_f32_e32 v199, v107, v198
	v_fmac_f32_e32 v215, v123, v214
	v_mul_f32_e32 v75, v74, v75
	v_mul_f32_e32 v91, v90, v91
	v_mul_f32_e32 v107, v106, v107
	v_mul_f32_e32 v123, v122, v123
	v_fmac_f32_e32 v168, v76, v167
	v_fmac_f32_e32 v184, v92, v183
	v_fmac_f32_e32 v200, v108, v199
	v_fmac_f32_e32 v216, v124, v215
	v_mul_f32_e32 v76, v75, v76
	v_mul_f32_e32 v92, v91, v92
	v_mul_f32_e32 v108, v107, v108
	v_mul_f32_e32 v124, v123, v124
	v_fmac_f32_e32 v169, v77, v168
	v_fmac_f32_e32 v185, v93, v184
	v_fmac_f32_e32 v201, v109, v200
	v_fmac_f32_e32 v217, v125, v216
	v_mul_f32_e32 v77, v76, v77
	v_mul_f32_e32 v93, v92, v93
	v_mul_f32_e32 v109, v108, v109
	v_mul_f32_e32 v125, v124, v125
	v_fmac_f32_e32 v170, v78, v169
	v_fmac_f32_e32 v186, v94, v185
	v_fmac_f32_e32 v202, v110, v201
	v_fmac_f32_e32 v218, v126, v217
	v_mul_f32_e32 v78, v77, v78
	v_mul_f32_e32 v94, v93, v94
	v_mul_f32_e32 v110, v109, v110
	v_mul_f32_e32 v126, v125, v126
	v_fmac_f32_e32 v171, v79, v170
	v_fmac_f32_e32 v187, v95, v186
	v_fmac_f32_e32 v203, v111, v202
	v_fmac_f32_e32 v219, v127, v218
	v_mul_f32_e32 v79, v78, v79
	v_mul_f32_e32 v95, v94, v95
	v_mul_f32_e32 v111, v110, v111
	v_mul_f32_e32 v127, v126, v127
	s_nop 1
	ds_bpermute_b32 v0, v225, v171
	ds_bpermute_b32 v1, v225, v79
	ds_bpermute_b32 v2, v226, v171
	ds_bpermute_b32 v3, v226, v79
	ds_bpermute_b32 v4, v227, v171
	ds_bpermute_b32 v5, v227, v79
	ds_bpermute_b32 v6, v225, v187
	ds_bpermute_b32 v7, v225, v95
	ds_bpermute_b32 v8, v226, v187
	ds_bpermute_b32 v9, v226, v95
	ds_bpermute_b32 v10, v227, v187
	ds_bpermute_b32 v11, v227, v95
	ds_bpermute_b32 v12, v225, v203
	ds_bpermute_b32 v13, v225, v111
	ds_bpermute_b32 v14, v226, v203
	ds_bpermute_b32 v15, v226, v111
	ds_bpermute_b32 v16, v227, v203
	ds_bpermute_b32 v17, v227, v111
	ds_bpermute_b32 v18, v225, v219
	ds_bpermute_b32 v19, v225, v127
	ds_bpermute_b32 v20, v226, v219
	ds_bpermute_b32 v21, v226, v127
	ds_bpermute_b32 v22, v227, v219
	ds_bpermute_b32 v23, v227, v127
	s_waitcnt lgkmcnt(0)
	v_cndmask_b32_e64 v4, 0, v4, s[98:99]
	v_cndmask_b32_e64 v5, 1.0, v5, s[98:99]
	v_cndmask_b32_e64 v2, 0, v2, s[96:97]
	v_cndmask_b32_e64 v3, 1.0, v3, s[96:97]
	v_cndmask_b32_e64 v0, 0, v0, s[94:95]
	v_cndmask_b32_e64 v1, 1.0, v1, s[94:95]
	v_cndmask_b32_e64 v10, 0, v10, s[98:99]
	v_cndmask_b32_e64 v11, 1.0, v11, s[98:99]
	v_cndmask_b32_e64 v8, 0, v8, s[96:97]
	v_cndmask_b32_e64 v9, 1.0, v9, s[96:97]
	v_cndmask_b32_e64 v6, 0, v6, s[94:95]
	v_cndmask_b32_e64 v7, 1.0, v7, s[94:95]
	v_cndmask_b32_e64 v16, 0, v16, s[98:99]
	v_cndmask_b32_e64 v17, 1.0, v17, s[98:99]
	v_cndmask_b32_e64 v14, 0, v14, s[96:97]
	v_cndmask_b32_e64 v15, 1.0, v15, s[96:97]
	v_cndmask_b32_e64 v12, 0, v12, s[94:95]
	v_cndmask_b32_e64 v13, 1.0, v13, s[94:95]
	v_cndmask_b32_e64 v22, 0, v22, s[98:99]
	v_cndmask_b32_e64 v23, 1.0, v23, s[98:99]
	v_cndmask_b32_e64 v20, 0, v20, s[96:97]
	v_cndmask_b32_e64 v21, 1.0, v21, s[96:97]
	v_cndmask_b32_e64 v18, 0, v18, s[94:95]
	v_cndmask_b32_e64 v19, 1.0, v19, s[94:95]
	v_fma_f32 v24, v3, v4, v2
	v_mul_f32_e32 v25, v5, v3
	v_fma_f32 v26, v9, v10, v8
	v_mul_f32_e32 v27, v11, v9
	v_fma_f32 v28, v15, v16, v14
	v_mul_f32_e32 v29, v17, v15
	v_fma_f32 v30, v21, v22, v20
	v_mul_f32_e32 v31, v23, v21
	v_fma_f32 v24, v1, v24, v0
	v_mul_f32_e32 v25, v25, v1
	v_fma_f32 v26, v7, v26, v6
	v_mul_f32_e32 v27, v27, v7
	v_fma_f32 v28, v13, v28, v12
	v_mul_f32_e32 v29, v29, v13
	v_fma_f32 v30, v19, v30, v18
	v_mul_f32_e32 v31, v31, v19
	v_fmac_f32_e32 v156, v64, v24
	v_fmac_f32_e32 v172, v80, v26
	v_fmac_f32_e32 v188, v96, v28
	v_fmac_f32_e32 v204, v112, v30
	v_mul_f32_e32 v64, v64, v25
	v_mul_f32_e32 v80, v80, v27
	v_mul_f32_e32 v96, v96, v29
	v_mul_f32_e32 v112, v112, v31
	v_fmac_f32_e32 v157, v65, v24
	v_fmac_f32_e32 v173, v81, v26
	v_fmac_f32_e32 v189, v97, v28
	v_fmac_f32_e32 v205, v113, v30
	v_mul_f32_e32 v65, v65, v25
	v_mul_f32_e32 v81, v81, v27
	v_mul_f32_e32 v97, v97, v29
	v_mul_f32_e32 v113, v113, v31
	v_fmac_f32_e32 v158, v66, v24
	v_fmac_f32_e32 v174, v82, v26
	v_fmac_f32_e32 v190, v98, v28
	v_fmac_f32_e32 v206, v114, v30
	v_mul_f32_e32 v66, v66, v25
	v_mul_f32_e32 v82, v82, v27
	v_mul_f32_e32 v98, v98, v29
	v_mul_f32_e32 v114, v114, v31
	v_fmac_f32_e32 v159, v67, v24
	v_fmac_f32_e32 v175, v83, v26
	v_fmac_f32_e32 v191, v99, v28
	v_fmac_f32_e32 v207, v115, v30
	v_mul_f32_e32 v67, v67, v25
	v_mul_f32_e32 v83, v83, v27
	v_mul_f32_e32 v99, v99, v29
	v_mul_f32_e32 v115, v115, v31
	v_fmac_f32_e32 v160, v68, v24
	v_fmac_f32_e32 v176, v84, v26
	v_fmac_f32_e32 v192, v100, v28
	v_fmac_f32_e32 v208, v116, v30
	v_mul_f32_e32 v68, v68, v25
	v_mul_f32_e32 v84, v84, v27
	v_mul_f32_e32 v100, v100, v29
	v_mul_f32_e32 v116, v116, v31
	v_fmac_f32_e32 v161, v69, v24
	v_fmac_f32_e32 v177, v85, v26
	v_fmac_f32_e32 v193, v101, v28
	v_fmac_f32_e32 v209, v117, v30
	v_mul_f32_e32 v69, v69, v25
	v_mul_f32_e32 v85, v85, v27
	v_mul_f32_e32 v101, v101, v29
	v_mul_f32_e32 v117, v117, v31
	v_fmac_f32_e32 v162, v70, v24
	v_fmac_f32_e32 v178, v86, v26
	v_fmac_f32_e32 v194, v102, v28
	v_fmac_f32_e32 v210, v118, v30
	v_mul_f32_e32 v70, v70, v25
	v_mul_f32_e32 v86, v86, v27
	v_mul_f32_e32 v102, v102, v29
	v_mul_f32_e32 v118, v118, v31
	v_fmac_f32_e32 v163, v71, v24
	v_fmac_f32_e32 v179, v87, v26
	v_fmac_f32_e32 v195, v103, v28
	v_fmac_f32_e32 v211, v119, v30
	v_mul_f32_e32 v71, v71, v25
	v_mul_f32_e32 v87, v87, v27
	v_mul_f32_e32 v103, v103, v29
	v_mul_f32_e32 v119, v119, v31
	v_fmac_f32_e32 v164, v72, v24
	v_fmac_f32_e32 v180, v88, v26
	v_fmac_f32_e32 v196, v104, v28
	v_fmac_f32_e32 v212, v120, v30
	v_mul_f32_e32 v72, v72, v25
	v_mul_f32_e32 v88, v88, v27
	v_mul_f32_e32 v104, v104, v29
	v_mul_f32_e32 v120, v120, v31
	v_fmac_f32_e32 v165, v73, v24
	v_fmac_f32_e32 v181, v89, v26
	v_fmac_f32_e32 v197, v105, v28
	v_fmac_f32_e32 v213, v121, v30
	v_mul_f32_e32 v73, v73, v25
	v_mul_f32_e32 v89, v89, v27
	v_mul_f32_e32 v105, v105, v29
	v_mul_f32_e32 v121, v121, v31
	v_fmac_f32_e32 v166, v74, v24
	v_fmac_f32_e32 v182, v90, v26
	v_fmac_f32_e32 v198, v106, v28
	v_fmac_f32_e32 v214, v122, v30
	v_mul_f32_e32 v74, v74, v25
	v_mul_f32_e32 v90, v90, v27
	v_mul_f32_e32 v106, v106, v29
	v_mul_f32_e32 v122, v122, v31
	v_fmac_f32_e32 v167, v75, v24
	v_fmac_f32_e32 v183, v91, v26
	v_fmac_f32_e32 v199, v107, v28
	v_fmac_f32_e32 v215, v123, v30
	v_mul_f32_e32 v75, v75, v25
	v_mul_f32_e32 v91, v91, v27
	v_mul_f32_e32 v107, v107, v29
	v_mul_f32_e32 v123, v123, v31
	v_fmac_f32_e32 v168, v76, v24
	v_fmac_f32_e32 v184, v92, v26
	v_fmac_f32_e32 v200, v108, v28
	v_fmac_f32_e32 v216, v124, v30
	v_mul_f32_e32 v76, v76, v25
	v_mul_f32_e32 v92, v92, v27
	v_mul_f32_e32 v108, v108, v29
	v_mul_f32_e32 v124, v124, v31
	v_fmac_f32_e32 v169, v77, v24
	v_fmac_f32_e32 v185, v93, v26
	v_fmac_f32_e32 v201, v109, v28
	v_fmac_f32_e32 v217, v125, v30
	v_mul_f32_e32 v77, v77, v25
	v_mul_f32_e32 v93, v93, v27
	v_mul_f32_e32 v109, v109, v29
	v_mul_f32_e32 v125, v125, v31
	v_fmac_f32_e32 v170, v78, v24
	v_fmac_f32_e32 v186, v94, v26
	v_fmac_f32_e32 v202, v110, v28
	v_fmac_f32_e32 v218, v126, v30
	v_mul_f32_e32 v78, v78, v25
	v_mul_f32_e32 v94, v94, v27
	v_mul_f32_e32 v110, v110, v29
	v_mul_f32_e32 v126, v126, v31
	v_fmac_f32_e32 v171, v79, v24
	v_fmac_f32_e32 v187, v95, v26
	v_fmac_f32_e32 v203, v111, v28
	v_fmac_f32_e32 v219, v127, v30
	v_mul_f32_e32 v79, v79, v25
	v_mul_f32_e32 v95, v95, v27
	v_mul_f32_e32 v111, v111, v29
	v_mul_f32_e32 v127, v127, v31
	s_mov_b64 exec, s[98:99]
	global_store_dword v224, v79, s[14:15]
	global_store_dword v224, v171, s[16:17]
	global_store_dword v224, v95, s[14:15] offset:64
	global_store_dword v224, v187, s[16:17] offset:64
	global_store_dword v224, v111, s[14:15] offset:128
	global_store_dword v224, v203, s[16:17] offset:128
	global_store_dword v224, v127, s[14:15] offset:192
	global_store_dword v224, v219, s[16:17] offset:192
	s_mov_b64 exec, -1
	v_cvt_pk_bf16_f32 v0, v156, v157
	v_cvt_pk_bf16_f32 v1, v64, v65
	ds_write_b16 v147, v0 offset:0
	ds_write_b16_d16_hi v147, v0 offset:1040
	ds_write_b16 v220, v1 offset:0
	ds_write_b16_d16_hi v220, v1 offset:128
	v_cvt_pk_bf16_f32 v2, v158, v159
	v_cvt_pk_bf16_f32 v3, v66, v67
	ds_write_b16 v147, v2 offset:2080
	ds_write_b16_d16_hi v147, v2 offset:3120
	ds_write_b16 v220, v3 offset:256
	ds_write_b16_d16_hi v220, v3 offset:384
	v_cvt_pk_bf16_f32 v4, v160, v161
	v_cvt_pk_bf16_f32 v5, v68, v69
	ds_write_b16 v147, v4 offset:4160
	ds_write_b16_d16_hi v147, v4 offset:5200
	ds_write_b16 v220, v5 offset:512
	ds_write_b16_d16_hi v220, v5 offset:640
	v_cvt_pk_bf16_f32 v6, v162, v163
	v_cvt_pk_bf16_f32 v7, v70, v71
	ds_write_b16 v147, v6 offset:6240
	ds_write_b16_d16_hi v147, v6 offset:7280
	ds_write_b16 v220, v7 offset:768
	ds_write_b16_d16_hi v220, v7 offset:896
	v_cvt_pk_bf16_f32 v8, v164, v165
	v_cvt_pk_bf16_f32 v9, v72, v73
	ds_write_b16 v147, v8 offset:8320
	ds_write_b16_d16_hi v147, v8 offset:9360
	ds_write_b16 v220, v9 offset:1024
	ds_write_b16_d16_hi v220, v9 offset:1152
	v_cvt_pk_bf16_f32 v10, v166, v167
	v_cvt_pk_bf16_f32 v11, v74, v75
	ds_write_b16 v147, v10 offset:10400
	ds_write_b16_d16_hi v147, v10 offset:11440
	ds_write_b16 v220, v11 offset:1280
	ds_write_b16_d16_hi v220, v11 offset:1408
	v_cvt_pk_bf16_f32 v12, v168, v169
	v_cvt_pk_bf16_f32 v13, v76, v77
	ds_write_b16 v147, v12 offset:12480
	ds_write_b16_d16_hi v147, v12 offset:13520
	ds_write_b16 v220, v13 offset:1536
	ds_write_b16_d16_hi v220, v13 offset:1664
	v_cvt_pk_bf16_f32 v14, v170, v171
	v_cvt_pk_bf16_f32 v15, v78, v79
	ds_write_b16 v147, v14 offset:14560
	ds_write_b16_d16_hi v147, v14 offset:15600
	ds_write_b16 v220, v15 offset:1792
	ds_write_b16_d16_hi v220, v15 offset:1920
	v_cvt_pk_bf16_f32 v16, v172, v173
	v_cvt_pk_bf16_f32 v17, v80, v81
	ds_write_b16 v147, v16 offset:32
	ds_write_b16_d16_hi v147, v16 offset:1072
	ds_write_b16 v220, v17 offset:32
	ds_write_b16_d16_hi v220, v17 offset:160
	v_cvt_pk_bf16_f32 v18, v174, v175
	v_cvt_pk_bf16_f32 v19, v82, v83
	ds_write_b16 v147, v18 offset:2112
	ds_write_b16_d16_hi v147, v18 offset:3152
	ds_write_b16 v220, v19 offset:288
	ds_write_b16_d16_hi v220, v19 offset:416
	v_cvt_pk_bf16_f32 v20, v176, v177
	v_cvt_pk_bf16_f32 v21, v84, v85
	ds_write_b16 v147, v20 offset:4192
	ds_write_b16_d16_hi v147, v20 offset:5232
	ds_write_b16 v220, v21 offset:544
	ds_write_b16_d16_hi v220, v21 offset:672
	v_cvt_pk_bf16_f32 v22, v178, v179
	v_cvt_pk_bf16_f32 v23, v86, v87
	ds_write_b16 v147, v22 offset:6272
	ds_write_b16_d16_hi v147, v22 offset:7312
	ds_write_b16 v220, v23 offset:800
	ds_write_b16_d16_hi v220, v23 offset:928
	v_cvt_pk_bf16_f32 v0, v180, v181
	v_cvt_pk_bf16_f32 v1, v88, v89
	ds_write_b16 v147, v0 offset:8352
	ds_write_b16_d16_hi v147, v0 offset:9392
	ds_write_b16 v220, v1 offset:1056
	ds_write_b16_d16_hi v220, v1 offset:1184
	v_cvt_pk_bf16_f32 v2, v182, v183
	v_cvt_pk_bf16_f32 v3, v90, v91
	ds_write_b16 v147, v2 offset:10432
	ds_write_b16_d16_hi v147, v2 offset:11472
	ds_write_b16 v220, v3 offset:1312
	ds_write_b16_d16_hi v220, v3 offset:1440
	v_cvt_pk_bf16_f32 v4, v184, v185
	v_cvt_pk_bf16_f32 v5, v92, v93
	ds_write_b16 v147, v4 offset:12512
	ds_write_b16_d16_hi v147, v4 offset:13552
	ds_write_b16 v220, v5 offset:1568
	ds_write_b16_d16_hi v220, v5 offset:1696
	v_cvt_pk_bf16_f32 v6, v186, v187
	v_cvt_pk_bf16_f32 v7, v94, v95
	ds_write_b16 v147, v6 offset:14592
	ds_write_b16_d16_hi v147, v6 offset:15632
	ds_write_b16 v220, v7 offset:1824
	ds_write_b16_d16_hi v220, v7 offset:1952
	v_cvt_pk_bf16_f32 v8, v188, v189
	v_cvt_pk_bf16_f32 v9, v96, v97
	ds_write_b16 v147, v8 offset:64
	ds_write_b16_d16_hi v147, v8 offset:1104
	ds_write_b16 v220, v9 offset:64
	ds_write_b16_d16_hi v220, v9 offset:192
	v_cvt_pk_bf16_f32 v10, v190, v191
	v_cvt_pk_bf16_f32 v11, v98, v99
	ds_write_b16 v147, v10 offset:2144
	ds_write_b16_d16_hi v147, v10 offset:3184
	ds_write_b16 v220, v11 offset:320
	ds_write_b16_d16_hi v220, v11 offset:448
	v_cvt_pk_bf16_f32 v12, v192, v193
	v_cvt_pk_bf16_f32 v13, v100, v101
	ds_write_b16 v147, v12 offset:4224
	ds_write_b16_d16_hi v147, v12 offset:5264
	ds_write_b16 v220, v13 offset:576
	ds_write_b16_d16_hi v220, v13 offset:704
	v_cvt_pk_bf16_f32 v14, v194, v195
	v_cvt_pk_bf16_f32 v15, v102, v103
	ds_write_b16 v147, v14 offset:6304
	ds_write_b16_d16_hi v147, v14 offset:7344
	ds_write_b16 v220, v15 offset:832
	ds_write_b16_d16_hi v220, v15 offset:960
	v_cvt_pk_bf16_f32 v16, v196, v197
	v_cvt_pk_bf16_f32 v17, v104, v105
	ds_write_b16 v147, v16 offset:8384
	ds_write_b16_d16_hi v147, v16 offset:9424
	ds_write_b16 v220, v17 offset:1088
	ds_write_b16_d16_hi v220, v17 offset:1216
	v_cvt_pk_bf16_f32 v18, v198, v199
	v_cvt_pk_bf16_f32 v19, v106, v107
	ds_write_b16 v147, v18 offset:10464
	ds_write_b16_d16_hi v147, v18 offset:11504
	ds_write_b16 v220, v19 offset:1344
	ds_write_b16_d16_hi v220, v19 offset:1472
	v_cvt_pk_bf16_f32 v20, v200, v201
	v_cvt_pk_bf16_f32 v21, v108, v109
	ds_write_b16 v147, v20 offset:12544
	ds_write_b16_d16_hi v147, v20 offset:13584
	ds_write_b16 v220, v21 offset:1600
	ds_write_b16_d16_hi v220, v21 offset:1728
	v_cvt_pk_bf16_f32 v22, v202, v203
	v_cvt_pk_bf16_f32 v23, v110, v111
	ds_write_b16 v147, v22 offset:14624
	ds_write_b16_d16_hi v147, v22 offset:15664
	ds_write_b16 v220, v23 offset:1856
	ds_write_b16_d16_hi v220, v23 offset:1984
	v_cvt_pk_bf16_f32 v0, v204, v205
	v_cvt_pk_bf16_f32 v1, v112, v113
	ds_write_b16 v147, v0 offset:96
	ds_write_b16_d16_hi v147, v0 offset:1136
	ds_write_b16 v220, v1 offset:96
	ds_write_b16_d16_hi v220, v1 offset:224
	v_cvt_pk_bf16_f32 v2, v206, v207
	v_cvt_pk_bf16_f32 v3, v114, v115
	ds_write_b16 v147, v2 offset:2176
	ds_write_b16_d16_hi v147, v2 offset:3216
	ds_write_b16 v220, v3 offset:352
	ds_write_b16_d16_hi v220, v3 offset:480
	v_cvt_pk_bf16_f32 v4, v208, v209
	v_cvt_pk_bf16_f32 v5, v116, v117
	ds_write_b16 v147, v4 offset:4256
	ds_write_b16_d16_hi v147, v4 offset:5296
	ds_write_b16 v220, v5 offset:608
	ds_write_b16_d16_hi v220, v5 offset:736
	v_cvt_pk_bf16_f32 v6, v210, v211
	v_cvt_pk_bf16_f32 v7, v118, v119
	ds_write_b16 v147, v6 offset:6336
	ds_write_b16_d16_hi v147, v6 offset:7376
	ds_write_b16 v220, v7 offset:864
	ds_write_b16_d16_hi v220, v7 offset:992
	v_cvt_pk_bf16_f32 v8, v212, v213
	v_cvt_pk_bf16_f32 v9, v120, v121
	ds_write_b16 v147, v8 offset:8416
	ds_write_b16_d16_hi v147, v8 offset:9456
	ds_write_b16 v220, v9 offset:1120
	ds_write_b16_d16_hi v220, v9 offset:1248
	v_cvt_pk_bf16_f32 v10, v214, v215
	v_cvt_pk_bf16_f32 v11, v122, v123
	ds_write_b16 v147, v10 offset:10496
	ds_write_b16_d16_hi v147, v10 offset:11536
	ds_write_b16 v220, v11 offset:1376
	ds_write_b16_d16_hi v220, v11 offset:1504
	v_cvt_pk_bf16_f32 v12, v216, v217
	v_cvt_pk_bf16_f32 v13, v124, v125
	ds_write_b16 v147, v12 offset:12576
	ds_write_b16_d16_hi v147, v12 offset:13616
	ds_write_b16 v220, v13 offset:1632
	ds_write_b16_d16_hi v220, v13 offset:1760
	v_cvt_pk_bf16_f32 v14, v218, v219
	v_cvt_pk_bf16_f32 v15, v126, v127
	ds_write_b16 v147, v14 offset:14656
	ds_write_b16_d16_hi v147, v14 offset:15696
	ds_write_b16 v220, v15 offset:1888
	ds_write_b16_d16_hi v220, v15 offset:2016
	ds_read_b128 v[64:67], v221
	ds_read_b128 v[68:71], v222
	ds_read_b128 v[72:75], v221 offset:8320
	ds_read_b128 v[76:79], v222 offset:1024
	ds_read_b128 v[80:83], v221 offset:16640
	ds_read_b128 v[84:87], v222 offset:2048
	ds_read_b128 v[88:91], v221 offset:24960
	ds_read_b128 v[92:95], v222 offset:3072
	ds_read_b128 v[96:99], v221 offset:33280
	ds_read_b128 v[100:103], v222 offset:4096
	ds_read_b128 v[104:107], v221 offset:41600
	ds_read_b128 v[108:111], v222 offset:5120
	ds_read_b128 v[112:115], v221 offset:49920
	ds_read_b128 v[116:119], v222 offset:6144
	ds_read_b128 v[120:123], v221 offset:58240
	ds_read_b128 v[124:127], v222 offset:7168
	v_add_u32_e32 v229, 0x2000, v223
	v_add_u32_e32 v230, 0x4000, v223
	v_add_u32_e32 v231, 0x6000, v223
	v_add_u32_e32 v232, 0x8000, v223
	v_add_u32_e32 v233, 0xa000, v223
	v_add_u32_e32 v234, 0xc000, v223
	v_add_u32_e32 v235, 0xe000, v223
	s_waitcnt lgkmcnt(15)
	global_store_dwordx4 v223, v[64:67], s[10:11]
	s_waitcnt lgkmcnt(14)
	global_store_dwordx4 v223, v[68:71], s[12:13]
	s_waitcnt lgkmcnt(13)
	global_store_dwordx4 v229, v[72:75], s[10:11]
	s_waitcnt lgkmcnt(12)
	global_store_dwordx4 v229, v[76:79], s[12:13]
	s_waitcnt lgkmcnt(11)
	global_store_dwordx4 v230, v[80:83], s[10:11]
	s_waitcnt lgkmcnt(10)
	global_store_dwordx4 v230, v[84:87], s[12:13]
	s_waitcnt lgkmcnt(9)
	global_store_dwordx4 v231, v[88:91], s[10:11]
	s_waitcnt lgkmcnt(8)
	global_store_dwordx4 v231, v[92:95], s[12:13]
	s_waitcnt lgkmcnt(7)
	global_store_dwordx4 v232, v[96:99], s[10:11]
	s_waitcnt lgkmcnt(6)
	global_store_dwordx4 v232, v[100:103], s[12:13]
	s_waitcnt lgkmcnt(5)
	global_store_dwordx4 v233, v[104:107], s[10:11]
	s_waitcnt lgkmcnt(4)
	global_store_dwordx4 v233, v[108:111], s[12:13]
	s_waitcnt lgkmcnt(3)
	global_store_dwordx4 v234, v[112:115], s[10:11]
	s_waitcnt lgkmcnt(2)
	global_store_dwordx4 v234, v[116:119], s[12:13]
	s_waitcnt lgkmcnt(1)
	global_store_dwordx4 v235, v[120:123], s[10:11]
	s_waitcnt lgkmcnt(0)
	global_store_dwordx4 v235, v[124:127], s[12:13]
	s_branch .LBB0_303
